# plus bf16 GEMM K-loops reordered so each accumulator's two MFMAs are back-to-back
# speedup vs baseline: 1.0125x; 1.0095x over previous
.LBB0_216:
	ds_read_b128 v[152:155], v160
	ds_read_b128 v[164:167], v160 offset:1024
	ds_read_b128 v[168:171], v160 offset:2048
	ds_read_b128 v[172:175], v160 offset:3072
	ds_read_b128 v[176:179], v161
	ds_read_b128 v[180:183], v161 offset:1024
	ds_read_b128 v[184:187], v161 offset:2048
	ds_read_b128 v[188:191], v161 offset:3072
	s_add_u32 s20, s0, 0xfff00080
	s_addc_u32 s21, s1, -1
	s_cmp_eq_u32 s30, 60
	s_cselect_b32 s23, s13, s21
	s_cselect_b32 s22, s24, s20
	s_cselect_b32 s21, s15, s29
	s_cselect_b32 s20, s25, s27
	s_add_i32 m0, s39, 0xc000
	ds_read_b128 v[192:195], v162
	ds_read_b128 v[196:199], v162 offset:1024
	ds_read_b128 v[200:203], v162 offset:2048
	ds_read_b128 v[204:207], v162 offset:3072
	ds_read_b128 v[208:211], v162 offset:4096
	ds_read_b128 v[212:215], v162 offset:5120
	ds_read_b128 v[216:219], v162 offset:6144
	ds_read_b128 v[220:223], v162 offset:7168
	global_load_lds_dwordx4 v140, s[0:1]
	s_add_i32 m0, s39, 0xe000
	s_nop 0
	global_load_lds_dwordx4 v142, s[0:1]
	s_waitcnt vmcnt(8)
	s_waitcnt lgkmcnt(0)
	s_barrier
	s_setprio 1
	s_waitcnt lgkmcnt(0)
	v_mfma_f32_16x16x32_bf16 v[126:129], v[152:155], v[192:195], v[126:129]
	v_mfma_f32_16x16x32_bf16 v[126:129], v[164:167], v[196:199], v[126:129]
	v_mfma_f32_16x16x32_bf16 v[122:125], v[168:171], v[192:195], v[122:125]
	v_mfma_f32_16x16x32_bf16 v[122:125], v[172:175], v[196:199], v[122:125]
	v_mfma_f32_16x16x32_bf16 v[114:117], v[152:155], v[200:203], v[114:117]
	v_mfma_f32_16x16x32_bf16 v[114:117], v[164:167], v[204:207], v[114:117]
	v_mfma_f32_16x16x32_bf16 v[106:109], v[168:171], v[200:203], v[106:109]
	v_mfma_f32_16x16x32_bf16 v[106:109], v[172:175], v[204:207], v[106:109]
	v_mfma_f32_16x16x32_bf16 v[98:101], v[152:155], v[208:211], v[98:101]
	v_mfma_f32_16x16x32_bf16 v[98:101], v[164:167], v[212:215], v[98:101]
	v_mfma_f32_16x16x32_bf16 v[90:93], v[168:171], v[208:211], v[90:93]
	v_mfma_f32_16x16x32_bf16 v[90:93], v[172:175], v[212:215], v[90:93]
	v_mfma_f32_16x16x32_bf16 v[82:85], v[152:155], v[216:219], v[82:85]
	v_mfma_f32_16x16x32_bf16 v[82:85], v[164:167], v[220:223], v[82:85]
	v_mfma_f32_16x16x32_bf16 v[74:77], v[168:171], v[216:219], v[74:77]
	v_mfma_f32_16x16x32_bf16 v[74:77], v[172:175], v[220:223], v[74:77]
	s_setprio 0
	s_setprio 1
	v_mfma_f32_16x16x32_bf16 v[118:121], v[176:179], v[192:195], v[118:121]
	v_mfma_f32_16x16x32_bf16 v[118:121], v[180:183], v[196:199], v[118:121]
	v_mfma_f32_16x16x32_bf16 v[110:113], v[184:187], v[192:195], v[110:113]
	v_mfma_f32_16x16x32_bf16 v[110:113], v[188:191], v[196:199], v[110:113]
	v_mfma_f32_16x16x32_bf16 v[102:105], v[176:179], v[200:203], v[102:105]
	v_mfma_f32_16x16x32_bf16 v[102:105], v[180:183], v[204:207], v[102:105]
	v_mfma_f32_16x16x32_bf16 v[94:97], v[184:187], v[200:203], v[94:97]
	v_mfma_f32_16x16x32_bf16 v[94:97], v[188:191], v[204:207], v[94:97]
	v_mfma_f32_16x16x32_bf16 v[86:89], v[176:179], v[208:211], v[86:89]
	v_mfma_f32_16x16x32_bf16 v[86:89], v[180:183], v[212:215], v[86:89]
	v_mfma_f32_16x16x32_bf16 v[78:81], v[184:187], v[208:211], v[78:81]
	v_mfma_f32_16x16x32_bf16 v[78:81], v[188:191], v[212:215], v[78:81]
	v_mfma_f32_16x16x32_bf16 v[70:73], v[176:179], v[216:219], v[70:73]
	v_mfma_f32_16x16x32_bf16 v[70:73], v[180:183], v[220:223], v[70:73]
	v_mfma_f32_16x16x32_bf16 v[66:69], v[184:187], v[216:219], v[66:69]
	v_mfma_f32_16x16x32_bf16 v[66:69], v[188:191], v[220:223], v[66:69]
	s_setprio 0
	s_barrier
	s_add_i32 s31, s49, s38
	s_mov_b32 m0, s31
	ds_read_b128 v[192:195], v162 offset:16384
	ds_read_b128 v[196:199], v162 offset:17408
	ds_read_b128 v[200:203], v162 offset:18432
	ds_read_b128 v[204:207], v162 offset:19456
	ds_read_b128 v[208:211], v162 offset:20480
	ds_read_b128 v[212:215], v162 offset:21504
	ds_read_b128 v[216:219], v162 offset:22528
	ds_read_b128 v[220:223], v162 offset:23552
	global_load_lds_dwordx4 v132, s[20:21]
	s_add_i32 m0, s31, 0x2000
	s_add_u32 s34, s20, 0x100000
	s_addc_u32 s35, s21, 0
	s_add_i32 s31, s50, s38
	global_load_lds_dwordx4 v136, s[20:21]
	s_mov_b32 m0, s31
	global_load_lds_dwordx4 v132, s[34:35]
	s_add_i32 m0, s31, 0x2000
	s_nop 0
	global_load_lds_dwordx4 v136, s[34:35]
	s_mov_b32 m0, s39
	s_nop 0
	global_load_lds_dwordx4 v130, s[22:23]
	s_mov_b32 m0, s40
	s_nop 0
	global_load_lds_dwordx4 v134, s[22:23]
	s_waitcnt vmcnt(8)
	s_waitcnt lgkmcnt(0)
	s_barrier
	s_setprio 1
	s_waitcnt lgkmcnt(0)
	v_mfma_f32_16x16x32_bf16 v[62:65], v[152:155], v[192:195], v[62:65]
	v_mfma_f32_16x16x32_bf16 v[62:65], v[164:167], v[196:199], v[62:65]
	v_mfma_f32_16x16x32_bf16 v[58:61], v[168:171], v[192:195], v[58:61]
	v_mfma_f32_16x16x32_bf16 v[58:61], v[172:175], v[196:199], v[58:61]
	v_mfma_f32_16x16x32_bf16 v[46:49], v[152:155], v[200:203], v[46:49]
	v_mfma_f32_16x16x32_bf16 v[46:49], v[164:167], v[204:207], v[46:49]
	v_mfma_f32_16x16x32_bf16 v[42:45], v[168:171], v[200:203], v[42:45]
	v_mfma_f32_16x16x32_bf16 v[42:45], v[172:175], v[204:207], v[42:45]
	v_mfma_f32_16x16x32_bf16 v[30:33], v[152:155], v[208:211], v[30:33]
	v_mfma_f32_16x16x32_bf16 v[30:33], v[164:167], v[212:215], v[30:33]
	v_mfma_f32_16x16x32_bf16 v[26:29], v[168:171], v[208:211], v[26:29]
	v_mfma_f32_16x16x32_bf16 v[26:29], v[172:175], v[212:215], v[26:29]
	v_mfma_f32_16x16x32_bf16 v[14:17], v[152:155], v[216:219], v[14:17]
	v_mfma_f32_16x16x32_bf16 v[14:17], v[164:167], v[220:223], v[14:17]
	v_mfma_f32_16x16x32_bf16 v[10:13], v[168:171], v[216:219], v[10:13]
	v_mfma_f32_16x16x32_bf16 v[10:13], v[172:175], v[220:223], v[10:13]
	s_setprio 0
	s_setprio 1
	v_mfma_f32_16x16x32_bf16 v[54:57], v[176:179], v[192:195], v[54:57]
	v_mfma_f32_16x16x32_bf16 v[54:57], v[180:183], v[196:199], v[54:57]
	v_mfma_f32_16x16x32_bf16 v[50:53], v[184:187], v[192:195], v[50:53]
	v_mfma_f32_16x16x32_bf16 v[50:53], v[188:191], v[196:199], v[50:53]
	v_mfma_f32_16x16x32_bf16 v[38:41], v[176:179], v[200:203], v[38:41]
	v_mfma_f32_16x16x32_bf16 v[38:41], v[180:183], v[204:207], v[38:41]
	v_mfma_f32_16x16x32_bf16 v[34:37], v[184:187], v[200:203], v[34:37]
	v_mfma_f32_16x16x32_bf16 v[34:37], v[188:191], v[204:207], v[34:37]
	v_mfma_f32_16x16x32_bf16 v[22:25], v[176:179], v[208:211], v[22:25]
	v_mfma_f32_16x16x32_bf16 v[22:25], v[180:183], v[212:215], v[22:25]
	v_mfma_f32_16x16x32_bf16 v[18:21], v[184:187], v[208:211], v[18:21]
	v_mfma_f32_16x16x32_bf16 v[18:21], v[188:191], v[212:215], v[18:21]
	v_mfma_f32_16x16x32_bf16 v[6:9], v[176:179], v[216:219], v[6:9]
	v_mfma_f32_16x16x32_bf16 v[6:9], v[180:183], v[220:223], v[6:9]
	v_mfma_f32_16x16x32_bf16 v[2:5], v[184:187], v[216:219], v[2:5]
	v_mfma_f32_16x16x32_bf16 v[2:5], v[188:191], v[220:223], v[2:5]
	s_setprio 0
	s_barrier
	s_add_i32 s31, 0, 0x18000
	v_add_u32_e32 v138, s31, v158
	s_add_i32 s33, 0, 0x1c000
	ds_read_b128 v[152:155], v138
	ds_read_b128 v[164:167], v138 offset:1024
	ds_read_b128 v[168:171], v138 offset:2048
	ds_read_b128 v[172:175], v138 offset:3072
	v_add_u32_e32 v138, s33, v158
	ds_read_b128 v[176:179], v138
	ds_read_b128 v[180:183], v138 offset:1024
	ds_read_b128 v[184:187], v138 offset:2048
	ds_read_b128 v[188:191], v138 offset:3072
	s_add_u32 s98, s22, 0x80
	s_addc_u32 s99, s23, 0
	s_add_u32 s22, s22, 0x100000
	s_addc_u32 s23, s23, 0
	s_mov_b32 m0, s41
	ds_read_b128 v[192:195], v162 offset:32768
	ds_read_b128 v[196:199], v162 offset:33792
	ds_read_b128 v[200:203], v162 offset:34816
	ds_read_b128 v[204:207], v162 offset:35840
	ds_read_b128 v[208:211], v162 offset:36864
	ds_read_b128 v[212:215], v162 offset:37888
	ds_read_b128 v[216:219], v162 offset:38912
	ds_read_b128 v[220:223], v162 offset:39936
	global_load_lds_dwordx4 v130, s[22:23]
	s_mov_b32 m0, s42
	s_nop 0
	global_load_lds_dwordx4 v134, s[22:23]
	s_waitcnt vmcnt(8)
	s_waitcnt lgkmcnt(0)
	s_barrier
	s_setprio 1
	s_waitcnt lgkmcnt(0)
	v_mfma_f32_16x16x32_bf16 v[126:129], v[152:155], v[192:195], v[126:129]
	v_mfma_f32_16x16x32_bf16 v[126:129], v[164:167], v[196:199], v[126:129]
	v_mfma_f32_16x16x32_bf16 v[122:125], v[168:171], v[192:195], v[122:125]
	v_mfma_f32_16x16x32_bf16 v[122:125], v[172:175], v[196:199], v[122:125]
	v_mfma_f32_16x16x32_bf16 v[114:117], v[152:155], v[200:203], v[114:117]
	v_mfma_f32_16x16x32_bf16 v[114:117], v[164:167], v[204:207], v[114:117]
	v_mfma_f32_16x16x32_bf16 v[106:109], v[168:171], v[200:203], v[106:109]
	v_mfma_f32_16x16x32_bf16 v[106:109], v[172:175], v[204:207], v[106:109]
	v_mfma_f32_16x16x32_bf16 v[98:101], v[152:155], v[208:211], v[98:101]
	v_mfma_f32_16x16x32_bf16 v[98:101], v[164:167], v[212:215], v[98:101]
	v_mfma_f32_16x16x32_bf16 v[90:93], v[168:171], v[208:211], v[90:93]
	v_mfma_f32_16x16x32_bf16 v[90:93], v[172:175], v[212:215], v[90:93]
	v_mfma_f32_16x16x32_bf16 v[82:85], v[152:155], v[216:219], v[82:85]
	v_mfma_f32_16x16x32_bf16 v[82:85], v[164:167], v[220:223], v[82:85]
	v_mfma_f32_16x16x32_bf16 v[74:77], v[168:171], v[216:219], v[74:77]
	v_mfma_f32_16x16x32_bf16 v[74:77], v[172:175], v[220:223], v[74:77]
	s_setprio 0
	s_setprio 1
	v_mfma_f32_16x16x32_bf16 v[118:121], v[176:179], v[192:195], v[118:121]
	v_mfma_f32_16x16x32_bf16 v[118:121], v[180:183], v[196:199], v[118:121]
	v_mfma_f32_16x16x32_bf16 v[110:113], v[184:187], v[192:195], v[110:113]
	v_mfma_f32_16x16x32_bf16 v[110:113], v[188:191], v[196:199], v[110:113]
	v_mfma_f32_16x16x32_bf16 v[102:105], v[176:179], v[200:203], v[102:105]
	v_mfma_f32_16x16x32_bf16 v[102:105], v[180:183], v[204:207], v[102:105]
	v_mfma_f32_16x16x32_bf16 v[94:97], v[184:187], v[200:203], v[94:97]
	v_mfma_f32_16x16x32_bf16 v[94:97], v[188:191], v[204:207], v[94:97]
	v_mfma_f32_16x16x32_bf16 v[86:89], v[176:179], v[208:211], v[86:89]
	v_mfma_f32_16x16x32_bf16 v[86:89], v[180:183], v[212:215], v[86:89]
	v_mfma_f32_16x16x32_bf16 v[78:81], v[184:187], v[208:211], v[78:81]
	v_mfma_f32_16x16x32_bf16 v[78:81], v[188:191], v[212:215], v[78:81]
	v_mfma_f32_16x16x32_bf16 v[70:73], v[176:179], v[216:219], v[70:73]
	v_mfma_f32_16x16x32_bf16 v[70:73], v[180:183], v[220:223], v[70:73]
	v_mfma_f32_16x16x32_bf16 v[66:69], v[184:187], v[216:219], v[66:69]
	v_mfma_f32_16x16x32_bf16 v[66:69], v[188:191], v[220:223], v[66:69]
	s_setprio 0
	s_barrier
	s_add_i32 s22, s31, s38
	s_mov_b32 m0, s22
	ds_read_b128 v[192:195], v162 offset:49152
	ds_read_b128 v[196:199], v162 offset:50176
	ds_read_b128 v[200:203], v162 offset:51200
	ds_read_b128 v[204:207], v162 offset:52224
	ds_read_b128 v[208:211], v162 offset:53248
	ds_read_b128 v[212:215], v162 offset:54272
	ds_read_b128 v[216:219], v162 offset:55296
	ds_read_b128 v[220:223], v162 offset:56320
	s_add_u32 s20, s20, 0x80
	s_addc_u32 s21, s21, 0
	global_load_lds_dwordx4 v132, s[20:21]
	s_add_i32 m0, s22, 0x2000
	s_add_i32 s22, s33, s38
	global_load_lds_dwordx4 v136, s[20:21]
	s_add_u32 s20, s20, 0x100000
	s_addc_u32 s21, s21, 0
	s_mov_b32 m0, s22
	s_nop 0
	global_load_lds_dwordx4 v132, s[20:21]
	s_add_i32 m0, s22, 0x2000
	s_nop 0
	global_load_lds_dwordx4 v136, s[20:21]
	s_mov_b32 m0, s45
	s_nop 0
	global_load_lds_dwordx4 v130, s[98:99]
	s_mov_b32 m0, s46
	s_nop 0
	global_load_lds_dwordx4 v134, s[98:99]
	s_waitcnt vmcnt(8)
	s_waitcnt lgkmcnt(0)
	s_barrier
	s_setprio 1
	s_waitcnt lgkmcnt(0)
	v_mfma_f32_16x16x32_bf16 v[62:65], v[152:155], v[192:195], v[62:65]
	v_mfma_f32_16x16x32_bf16 v[62:65], v[164:167], v[196:199], v[62:65]
	v_mfma_f32_16x16x32_bf16 v[58:61], v[168:171], v[192:195], v[58:61]
	v_mfma_f32_16x16x32_bf16 v[58:61], v[172:175], v[196:199], v[58:61]
	v_mfma_f32_16x16x32_bf16 v[46:49], v[152:155], v[200:203], v[46:49]
	v_mfma_f32_16x16x32_bf16 v[46:49], v[164:167], v[204:207], v[46:49]
	v_mfma_f32_16x16x32_bf16 v[42:45], v[168:171], v[200:203], v[42:45]
	v_mfma_f32_16x16x32_bf16 v[42:45], v[172:175], v[204:207], v[42:45]
	v_mfma_f32_16x16x32_bf16 v[30:33], v[152:155], v[208:211], v[30:33]
	v_mfma_f32_16x16x32_bf16 v[30:33], v[164:167], v[212:215], v[30:33]
	v_mfma_f32_16x16x32_bf16 v[26:29], v[168:171], v[208:211], v[26:29]
	v_mfma_f32_16x16x32_bf16 v[26:29], v[172:175], v[212:215], v[26:29]
	v_mfma_f32_16x16x32_bf16 v[14:17], v[152:155], v[216:219], v[14:17]
	v_mfma_f32_16x16x32_bf16 v[14:17], v[164:167], v[220:223], v[14:17]
	v_mfma_f32_16x16x32_bf16 v[10:13], v[168:171], v[216:219], v[10:13]
	v_mfma_f32_16x16x32_bf16 v[10:13], v[172:175], v[220:223], v[10:13]
	s_setprio 0
	s_setprio 1
	v_mfma_f32_16x16x32_bf16 v[54:57], v[176:179], v[192:195], v[54:57]
	v_mfma_f32_16x16x32_bf16 v[54:57], v[180:183], v[196:199], v[54:57]
	v_mfma_f32_16x16x32_bf16 v[50:53], v[184:187], v[192:195], v[50:53]
	v_mfma_f32_16x16x32_bf16 v[50:53], v[188:191], v[196:199], v[50:53]
	v_mfma_f32_16x16x32_bf16 v[38:41], v[176:179], v[200:203], v[38:41]
	v_mfma_f32_16x16x32_bf16 v[38:41], v[180:183], v[204:207], v[38:41]
	v_mfma_f32_16x16x32_bf16 v[34:37], v[184:187], v[200:203], v[34:37]
	v_mfma_f32_16x16x32_bf16 v[34:37], v[188:191], v[204:207], v[34:37]
	v_mfma_f32_16x16x32_bf16 v[22:25], v[176:179], v[208:211], v[22:25]
	v_mfma_f32_16x16x32_bf16 v[22:25], v[180:183], v[212:215], v[22:25]
	v_mfma_f32_16x16x32_bf16 v[18:21], v[184:187], v[208:211], v[18:21]
	v_mfma_f32_16x16x32_bf16 v[18:21], v[188:191], v[212:215], v[18:21]
	v_mfma_f32_16x16x32_bf16 v[6:9], v[176:179], v[216:219], v[6:9]
	v_mfma_f32_16x16x32_bf16 v[6:9], v[180:183], v[220:223], v[6:9]
	v_mfma_f32_16x16x32_bf16 v[2:5], v[184:187], v[216:219], v[2:5]
	v_mfma_f32_16x16x32_bf16 v[2:5], v[188:191], v[220:223], v[2:5]
	s_setprio 0
	s_barrier
	s_add_i32 s30, s30, 2
	s_add_u32 s0, s0, 0x100
	s_addc_u32 s1, s1, 0
	s_add_u32 s27, s27, 0x100
	s_addc_u32 s29, s29, 0
	s_cmp_gt_u32 s30, 61
	s_cbranch_scc0 .LBB0_216
	s_and_b64 vcc, exec, s[10:11]
	s_cbranch_vccz .LBB0_219
	s_barrier

.LBB0_863:
	ds_read_b128 v[146:149], v154
	ds_read_b128 v[158:161], v154 offset:1024
	ds_read_b128 v[162:165], v154 offset:2048
	ds_read_b128 v[166:169], v154 offset:3072
	ds_read_b128 v[170:173], v155
	ds_read_b128 v[174:177], v155 offset:1024
	ds_read_b128 v[178:181], v155 offset:2048
	ds_read_b128 v[182:185], v155 offset:3072
	s_add_u32 s22, s20, 0xfff80080
	s_addc_u32 s23, s21, -1
	s_cmp_eq_u32 s43, 28
	s_cselect_b32 s25, s13, s23
	s_cselect_b32 s24, s39, s22
	s_cselect_b32 s23, s11, s42
	s_cselect_b32 s22, s40, s41
	s_add_i32 m0, s19, 0xc000
	ds_read_b128 v[186:189], v156
	ds_read_b128 v[190:193], v156 offset:1024
	ds_read_b128 v[194:197], v156 offset:2048
	ds_read_b128 v[198:201], v156 offset:3072
	ds_read_b128 v[202:205], v156 offset:4096
	ds_read_b128 v[206:209], v156 offset:5120
	ds_read_b128 v[210:213], v156 offset:6144
	ds_read_b128 v[214:217], v156 offset:7168
	global_load_lds_dwordx4 v138, s[20:21]
	s_add_i32 m0, s19, 0xe000
	s_nop 0
	global_load_lds_dwordx4 v140, s[20:21]
	s_waitcnt vmcnt(8)
	s_waitcnt lgkmcnt(0)
	s_barrier
	s_setprio 1
	s_waitcnt lgkmcnt(0)
	v_mfma_f32_16x16x32_bf16 v[126:129], v[146:149], v[186:189], v[126:129]
	v_mfma_f32_16x16x32_bf16 v[126:129], v[158:161], v[190:193], v[126:129]
	v_mfma_f32_16x16x32_bf16 v[122:125], v[162:165], v[186:189], v[122:125]
	v_mfma_f32_16x16x32_bf16 v[122:125], v[166:169], v[190:193], v[122:125]
	v_mfma_f32_16x16x32_bf16 v[110:113], v[146:149], v[194:197], v[110:113]
	v_mfma_f32_16x16x32_bf16 v[110:113], v[158:161], v[198:201], v[110:113]
	v_mfma_f32_16x16x32_bf16 v[106:109], v[162:165], v[194:197], v[106:109]
	v_mfma_f32_16x16x32_bf16 v[106:109], v[166:169], v[198:201], v[106:109]
	v_mfma_f32_16x16x32_bf16 v[94:97], v[146:149], v[202:205], v[94:97]
	v_mfma_f32_16x16x32_bf16 v[94:97], v[158:161], v[206:209], v[94:97]
	v_mfma_f32_16x16x32_bf16 v[90:93], v[162:165], v[202:205], v[90:93]
	v_mfma_f32_16x16x32_bf16 v[90:93], v[166:169], v[206:209], v[90:93]
	v_mfma_f32_16x16x32_bf16 v[78:81], v[146:149], v[210:213], v[78:81]
	v_mfma_f32_16x16x32_bf16 v[78:81], v[158:161], v[214:217], v[78:81]
	v_mfma_f32_16x16x32_bf16 v[74:77], v[162:165], v[210:213], v[74:77]
	v_mfma_f32_16x16x32_bf16 v[74:77], v[166:169], v[214:217], v[74:77]
	s_setprio 0
	s_setprio 1
	v_mfma_f32_16x16x32_bf16 v[118:121], v[170:173], v[186:189], v[118:121]
	v_mfma_f32_16x16x32_bf16 v[118:121], v[174:177], v[190:193], v[118:121]
	v_mfma_f32_16x16x32_bf16 v[114:117], v[178:181], v[186:189], v[114:117]
	v_mfma_f32_16x16x32_bf16 v[114:117], v[182:185], v[190:193], v[114:117]
	v_mfma_f32_16x16x32_bf16 v[102:105], v[170:173], v[194:197], v[102:105]
	v_mfma_f32_16x16x32_bf16 v[102:105], v[174:177], v[198:201], v[102:105]
	v_mfma_f32_16x16x32_bf16 v[98:101], v[178:181], v[194:197], v[98:101]
	v_mfma_f32_16x16x32_bf16 v[98:101], v[182:185], v[198:201], v[98:101]
	v_mfma_f32_16x16x32_bf16 v[86:89], v[170:173], v[202:205], v[86:89]
	v_mfma_f32_16x16x32_bf16 v[86:89], v[174:177], v[206:209], v[86:89]
	v_mfma_f32_16x16x32_bf16 v[82:85], v[178:181], v[202:205], v[82:85]
	v_mfma_f32_16x16x32_bf16 v[82:85], v[182:185], v[206:209], v[82:85]
	v_mfma_f32_16x16x32_bf16 v[70:73], v[170:173], v[210:213], v[70:73]
	v_mfma_f32_16x16x32_bf16 v[70:73], v[174:177], v[214:217], v[70:73]
	v_mfma_f32_16x16x32_bf16 v[66:69], v[178:181], v[210:213], v[66:69]
	v_mfma_f32_16x16x32_bf16 v[66:69], v[182:185], v[214:217], v[66:69]
	s_setprio 0
	s_barrier
	s_add_i32 s44, s36, s27
	s_mov_b32 m0, s44
	ds_read_b128 v[186:189], v156 offset:16384
	ds_read_b128 v[190:193], v156 offset:17408
	ds_read_b128 v[194:197], v156 offset:18432
	ds_read_b128 v[198:201], v156 offset:19456
	ds_read_b128 v[202:205], v156 offset:20480
	ds_read_b128 v[206:209], v156 offset:21504
	ds_read_b128 v[210:213], v156 offset:22528
	ds_read_b128 v[214:217], v156 offset:23552
	global_load_lds_dwordx4 v132, s[22:23]
	s_add_i32 m0, s44, 0x2000
	s_add_u32 s44, s22, 0x80000
	s_addc_u32 s45, s23, 0
	s_add_i32 s46, s37, s27
	global_load_lds_dwordx4 v136, s[22:23]
	s_mov_b32 m0, s46
	global_load_lds_dwordx4 v132, s[44:45]
	s_add_i32 m0, s46, 0x2000
	s_nop 0
	global_load_lds_dwordx4 v136, s[44:45]
	s_mov_b32 m0, s19
	s_nop 0
	global_load_lds_dwordx4 v130, s[24:25]
	s_mov_b32 m0, s28
	s_nop 0
	global_load_lds_dwordx4 v134, s[24:25]
	s_waitcnt vmcnt(8)
	s_waitcnt lgkmcnt(0)
	s_barrier
	s_setprio 1
	s_waitcnt lgkmcnt(0)
	v_mfma_f32_16x16x32_bf16 v[62:65], v[146:149], v[186:189], v[62:65]
	v_mfma_f32_16x16x32_bf16 v[62:65], v[158:161], v[190:193], v[62:65]
	v_mfma_f32_16x16x32_bf16 v[58:61], v[162:165], v[186:189], v[58:61]
	v_mfma_f32_16x16x32_bf16 v[58:61], v[166:169], v[190:193], v[58:61]
	v_mfma_f32_16x16x32_bf16 v[46:49], v[146:149], v[194:197], v[46:49]
	v_mfma_f32_16x16x32_bf16 v[46:49], v[158:161], v[198:201], v[46:49]
	v_mfma_f32_16x16x32_bf16 v[42:45], v[162:165], v[194:197], v[42:45]
	v_mfma_f32_16x16x32_bf16 v[42:45], v[166:169], v[198:201], v[42:45]
	v_mfma_f32_16x16x32_bf16 v[30:33], v[146:149], v[202:205], v[30:33]
	v_mfma_f32_16x16x32_bf16 v[30:33], v[158:161], v[206:209], v[30:33]
	v_mfma_f32_16x16x32_bf16 v[26:29], v[162:165], v[202:205], v[26:29]
	v_mfma_f32_16x16x32_bf16 v[26:29], v[166:169], v[206:209], v[26:29]
	v_mfma_f32_16x16x32_bf16 v[14:17], v[146:149], v[210:213], v[14:17]
	v_mfma_f32_16x16x32_bf16 v[14:17], v[158:161], v[214:217], v[14:17]
	v_mfma_f32_16x16x32_bf16 v[10:13], v[162:165], v[210:213], v[10:13]
	v_mfma_f32_16x16x32_bf16 v[10:13], v[166:169], v[214:217], v[10:13]
	s_setprio 0
	s_setprio 1
	v_mfma_f32_16x16x32_bf16 v[54:57], v[170:173], v[186:189], v[54:57]
	v_mfma_f32_16x16x32_bf16 v[54:57], v[174:177], v[190:193], v[54:57]
	v_mfma_f32_16x16x32_bf16 v[50:53], v[178:181], v[186:189], v[50:53]
	v_mfma_f32_16x16x32_bf16 v[50:53], v[182:185], v[190:193], v[50:53]
	v_mfma_f32_16x16x32_bf16 v[38:41], v[170:173], v[194:197], v[38:41]
	v_mfma_f32_16x16x32_bf16 v[38:41], v[174:177], v[198:201], v[38:41]
	v_mfma_f32_16x16x32_bf16 v[34:37], v[178:181], v[194:197], v[34:37]
	v_mfma_f32_16x16x32_bf16 v[34:37], v[182:185], v[198:201], v[34:37]
	v_mfma_f32_16x16x32_bf16 v[22:25], v[170:173], v[202:205], v[22:25]
	v_mfma_f32_16x16x32_bf16 v[22:25], v[174:177], v[206:209], v[22:25]
	v_mfma_f32_16x16x32_bf16 v[18:21], v[178:181], v[202:205], v[18:21]
	v_mfma_f32_16x16x32_bf16 v[18:21], v[182:185], v[206:209], v[18:21]
	v_mfma_f32_16x16x32_bf16 v[6:9], v[170:173], v[210:213], v[6:9]
	v_mfma_f32_16x16x32_bf16 v[6:9], v[174:177], v[214:217], v[6:9]
	v_mfma_f32_16x16x32_bf16 v[2:5], v[178:181], v[210:213], v[2:5]
	v_mfma_f32_16x16x32_bf16 v[2:5], v[182:185], v[214:217], v[2:5]
	s_setprio 0
	s_barrier
	s_add_i32 s44, 0, 0x18000
	v_add_u32_e32 v157, s44, v152
	s_add_i32 s45, 0, 0x1c000
	ds_read_b128 v[146:149], v157
	ds_read_b128 v[158:161], v157 offset:1024
	ds_read_b128 v[162:165], v157 offset:2048
	ds_read_b128 v[166:169], v157 offset:3072
	v_add_u32_e32 v157, s45, v152
	ds_read_b128 v[170:173], v157
	ds_read_b128 v[174:177], v157 offset:1024
	ds_read_b128 v[178:181], v157 offset:2048
	ds_read_b128 v[182:185], v157 offset:3072
	s_add_u32 s98, s24, 0x80
	s_addc_u32 s99, s25, 0
	s_add_u32 s24, s24, 0x80000
	s_addc_u32 s25, s25, 0
	s_mov_b32 m0, s29
	ds_read_b128 v[186:189], v156 offset:32768
	ds_read_b128 v[190:193], v156 offset:33792
	ds_read_b128 v[194:197], v156 offset:34816
	ds_read_b128 v[198:201], v156 offset:35840
	ds_read_b128 v[202:205], v156 offset:36864
	ds_read_b128 v[206:209], v156 offset:37888
	ds_read_b128 v[210:213], v156 offset:38912
	ds_read_b128 v[214:217], v156 offset:39936
	global_load_lds_dwordx4 v130, s[24:25]
	s_mov_b32 m0, s30
	s_nop 0
	global_load_lds_dwordx4 v134, s[24:25]
	s_waitcnt vmcnt(8)
	s_waitcnt lgkmcnt(0)
	s_barrier
	s_setprio 1
	s_waitcnt lgkmcnt(0)
	v_mfma_f32_16x16x32_bf16 v[126:129], v[146:149], v[186:189], v[126:129]
	v_mfma_f32_16x16x32_bf16 v[126:129], v[158:161], v[190:193], v[126:129]
	v_mfma_f32_16x16x32_bf16 v[122:125], v[162:165], v[186:189], v[122:125]
	v_mfma_f32_16x16x32_bf16 v[122:125], v[166:169], v[190:193], v[122:125]
	v_mfma_f32_16x16x32_bf16 v[110:113], v[146:149], v[194:197], v[110:113]
	v_mfma_f32_16x16x32_bf16 v[110:113], v[158:161], v[198:201], v[110:113]
	v_mfma_f32_16x16x32_bf16 v[106:109], v[162:165], v[194:197], v[106:109]
	v_mfma_f32_16x16x32_bf16 v[106:109], v[166:169], v[198:201], v[106:109]
	v_mfma_f32_16x16x32_bf16 v[94:97], v[146:149], v[202:205], v[94:97]
	v_mfma_f32_16x16x32_bf16 v[94:97], v[158:161], v[206:209], v[94:97]
	v_mfma_f32_16x16x32_bf16 v[90:93], v[162:165], v[202:205], v[90:93]
	v_mfma_f32_16x16x32_bf16 v[90:93], v[166:169], v[206:209], v[90:93]
	v_mfma_f32_16x16x32_bf16 v[78:81], v[146:149], v[210:213], v[78:81]
	v_mfma_f32_16x16x32_bf16 v[78:81], v[158:161], v[214:217], v[78:81]
	v_mfma_f32_16x16x32_bf16 v[74:77], v[162:165], v[210:213], v[74:77]
	v_mfma_f32_16x16x32_bf16 v[74:77], v[166:169], v[214:217], v[74:77]
	s_setprio 0
	s_setprio 1
	v_mfma_f32_16x16x32_bf16 v[118:121], v[170:173], v[186:189], v[118:121]
	v_mfma_f32_16x16x32_bf16 v[118:121], v[174:177], v[190:193], v[118:121]
	v_mfma_f32_16x16x32_bf16 v[114:117], v[178:181], v[186:189], v[114:117]
	v_mfma_f32_16x16x32_bf16 v[114:117], v[182:185], v[190:193], v[114:117]
	v_mfma_f32_16x16x32_bf16 v[102:105], v[170:173], v[194:197], v[102:105]
	v_mfma_f32_16x16x32_bf16 v[102:105], v[174:177], v[198:201], v[102:105]
	v_mfma_f32_16x16x32_bf16 v[98:101], v[178:181], v[194:197], v[98:101]
	v_mfma_f32_16x16x32_bf16 v[98:101], v[182:185], v[198:201], v[98:101]
	v_mfma_f32_16x16x32_bf16 v[86:89], v[170:173], v[202:205], v[86:89]
	v_mfma_f32_16x16x32_bf16 v[86:89], v[174:177], v[206:209], v[86:89]
	v_mfma_f32_16x16x32_bf16 v[82:85], v[178:181], v[202:205], v[82:85]
	v_mfma_f32_16x16x32_bf16 v[82:85], v[182:185], v[206:209], v[82:85]
	v_mfma_f32_16x16x32_bf16 v[70:73], v[170:173], v[210:213], v[70:73]
	v_mfma_f32_16x16x32_bf16 v[70:73], v[174:177], v[214:217], v[70:73]
	v_mfma_f32_16x16x32_bf16 v[66:69], v[178:181], v[210:213], v[66:69]
	v_mfma_f32_16x16x32_bf16 v[66:69], v[182:185], v[214:217], v[66:69]
	s_setprio 0
	s_barrier
	s_add_i32 s24, s44, s27
	s_mov_b32 m0, s24
	ds_read_b128 v[186:189], v156 offset:49152
	ds_read_b128 v[190:193], v156 offset:50176
	ds_read_b128 v[194:197], v156 offset:51200
	ds_read_b128 v[198:201], v156 offset:52224
	ds_read_b128 v[202:205], v156 offset:53248
	ds_read_b128 v[206:209], v156 offset:54272
	ds_read_b128 v[210:213], v156 offset:55296
	ds_read_b128 v[214:217], v156 offset:56320
	s_add_u32 s22, s22, 0x80
	s_addc_u32 s23, s23, 0
	global_load_lds_dwordx4 v132, s[22:23]
	s_add_i32 m0, s24, 0x2000
	s_add_i32 s24, s45, s27
	global_load_lds_dwordx4 v136, s[22:23]
	s_add_u32 s22, s22, 0x80000
	s_addc_u32 s23, s23, 0
	s_mov_b32 m0, s24
	s_nop 0
	global_load_lds_dwordx4 v132, s[22:23]
	s_add_i32 m0, s24, 0x2000
	s_nop 0
	global_load_lds_dwordx4 v136, s[22:23]
	s_mov_b32 m0, s33
	s_nop 0
	global_load_lds_dwordx4 v130, s[98:99]
	s_mov_b32 m0, s34
	s_nop 0
	global_load_lds_dwordx4 v134, s[98:99]
	s_waitcnt vmcnt(8)
	s_waitcnt lgkmcnt(0)
	s_barrier
	s_setprio 1
	s_waitcnt lgkmcnt(0)
	v_mfma_f32_16x16x32_bf16 v[62:65], v[146:149], v[186:189], v[62:65]
	v_mfma_f32_16x16x32_bf16 v[62:65], v[158:161], v[190:193], v[62:65]
	v_mfma_f32_16x16x32_bf16 v[58:61], v[162:165], v[186:189], v[58:61]
	v_mfma_f32_16x16x32_bf16 v[58:61], v[166:169], v[190:193], v[58:61]
	v_mfma_f32_16x16x32_bf16 v[46:49], v[146:149], v[194:197], v[46:49]
	v_mfma_f32_16x16x32_bf16 v[46:49], v[158:161], v[198:201], v[46:49]
	v_mfma_f32_16x16x32_bf16 v[42:45], v[162:165], v[194:197], v[42:45]
	v_mfma_f32_16x16x32_bf16 v[42:45], v[166:169], v[198:201], v[42:45]
	v_mfma_f32_16x16x32_bf16 v[30:33], v[146:149], v[202:205], v[30:33]
	v_mfma_f32_16x16x32_bf16 v[30:33], v[158:161], v[206:209], v[30:33]
	v_mfma_f32_16x16x32_bf16 v[26:29], v[162:165], v[202:205], v[26:29]
	v_mfma_f32_16x16x32_bf16 v[26:29], v[166:169], v[206:209], v[26:29]
	v_mfma_f32_16x16x32_bf16 v[14:17], v[146:149], v[210:213], v[14:17]
	v_mfma_f32_16x16x32_bf16 v[14:17], v[158:161], v[214:217], v[14:17]
	v_mfma_f32_16x16x32_bf16 v[10:13], v[162:165], v[210:213], v[10:13]
	v_mfma_f32_16x16x32_bf16 v[10:13], v[166:169], v[214:217], v[10:13]
	s_setprio 0
	s_setprio 1
	v_mfma_f32_16x16x32_bf16 v[54:57], v[170:173], v[186:189], v[54:57]
	v_mfma_f32_16x16x32_bf16 v[54:57], v[174:177], v[190:193], v[54:57]
	v_mfma_f32_16x16x32_bf16 v[50:53], v[178:181], v[186:189], v[50:53]
	v_mfma_f32_16x16x32_bf16 v[50:53], v[182:185], v[190:193], v[50:53]
	v_mfma_f32_16x16x32_bf16 v[38:41], v[170:173], v[194:197], v[38:41]
	v_mfma_f32_16x16x32_bf16 v[38:41], v[174:177], v[198:201], v[38:41]
	v_mfma_f32_16x16x32_bf16 v[34:37], v[178:181], v[194:197], v[34:37]
	v_mfma_f32_16x16x32_bf16 v[34:37], v[182:185], v[198:201], v[34:37]
	v_mfma_f32_16x16x32_bf16 v[22:25], v[170:173], v[202:205], v[22:25]
	v_mfma_f32_16x16x32_bf16 v[22:25], v[174:177], v[206:209], v[22:25]
	v_mfma_f32_16x16x32_bf16 v[18:21], v[178:181], v[202:205], v[18:21]
	v_mfma_f32_16x16x32_bf16 v[18:21], v[182:185], v[206:209], v[18:21]
	v_mfma_f32_16x16x32_bf16 v[6:9], v[170:173], v[210:213], v[6:9]
	v_mfma_f32_16x16x32_bf16 v[6:9], v[174:177], v[214:217], v[6:9]
	v_mfma_f32_16x16x32_bf16 v[2:5], v[178:181], v[210:213], v[2:5]
	v_mfma_f32_16x16x32_bf16 v[2:5], v[182:185], v[214:217], v[2:5]
	s_setprio 0
	s_barrier
	s_add_i32 s43, s43, 2
	s_add_u32 s20, s20, 0x100
	s_addc_u32 s21, s21, 0
	s_add_u32 s41, s41, 0x100
	s_addc_u32 s42, s42, 0
	s_cmp_gt_u32 s43, 29
	s_cbranch_scc0 .LBB0_863
	s_and_b64 vcc, exec, s[8:9]
	s_cbranch_vccz .LBB0_866
	s_barrier

.LBB0_941:
	ds_read_b128 v[90:93], v188
	ds_read_b128 v[94:97], v188 offset:1024
	ds_read_b128 v[102:105], v188 offset:2048
	ds_read_b128 v[110:113], v188 offset:3072
	ds_read_b128 v[146:149], v189
	ds_read_b128 v[150:153], v189 offset:1024
	ds_read_b128 v[154:157], v189 offset:2048
	ds_read_b128 v[158:161], v189 offset:3072
	s_add_u32 s30, s28, 0xfff00080
	s_addc_u32 s31, s29, -1
	s_cmp_eq_u32 s51, 60
	s_cselect_b32 s35, s21, s31
	s_cselect_b32 s34, s27, s30
	s_cselect_b32 s31, s19, s50
	s_cselect_b32 s30, s48, s49
	s_add_i32 m0, s36, 0xc000
	ds_read_b128 v[178:181], v190
	ds_read_b128 v[182:185], v190 offset:1024
	ds_read_b128 v[192:195], v190 offset:2048
	ds_read_b128 v[196:199], v190 offset:3072
	ds_read_b128 v[200:203], v190 offset:4096
	ds_read_b128 v[204:207], v190 offset:5120
	ds_read_b128 v[208:211], v190 offset:6144
	ds_read_b128 v[212:215], v190 offset:7168
	global_load_lds_dwordx4 v170, s[28:29]
	s_add_i32 m0, s36, 0xe000
	s_nop 0
	global_load_lds_dwordx4 v172, s[28:29]
	s_waitcnt vmcnt(8)
	s_waitcnt lgkmcnt(0)
	s_barrier
	s_setprio 1
	s_waitcnt lgkmcnt(0)
	v_mfma_f32_16x16x32_bf16 v[142:145], v[90:93], v[178:181], v[142:145]
	v_mfma_f32_16x16x32_bf16 v[142:145], v[94:97], v[182:185], v[142:145]
	v_mfma_f32_16x16x32_bf16 v[138:141], v[102:105], v[178:181], v[138:141]
	v_mfma_f32_16x16x32_bf16 v[138:141], v[110:113], v[182:185], v[138:141]
	v_mfma_f32_16x16x32_bf16 v[126:129], v[90:93], v[192:195], v[126:129]
	v_mfma_f32_16x16x32_bf16 v[126:129], v[94:97], v[196:199], v[126:129]
	v_mfma_f32_16x16x32_bf16 v[122:125], v[102:105], v[192:195], v[122:125]
	v_mfma_f32_16x16x32_bf16 v[122:125], v[110:113], v[196:199], v[122:125]
	v_mfma_f32_16x16x32_bf16 v[106:109], v[90:93], v[200:203], v[106:109]
	v_mfma_f32_16x16x32_bf16 v[106:109], v[94:97], v[204:207], v[106:109]
	v_mfma_f32_16x16x32_bf16 v[98:101], v[102:105], v[200:203], v[98:101]
	v_mfma_f32_16x16x32_bf16 v[98:101], v[110:113], v[204:207], v[98:101]
	v_mfma_f32_16x16x32_bf16 v[78:81], v[90:93], v[208:211], v[78:81]
	v_mfma_f32_16x16x32_bf16 v[78:81], v[94:97], v[212:215], v[78:81]
	v_mfma_f32_16x16x32_bf16 v[74:77], v[102:105], v[208:211], v[74:77]
	v_mfma_f32_16x16x32_bf16 v[74:77], v[110:113], v[212:215], v[74:77]
	s_setprio 0
	s_setprio 1
	v_mfma_f32_16x16x32_bf16 v[134:137], v[146:149], v[178:181], v[134:137]
	v_mfma_f32_16x16x32_bf16 v[134:137], v[150:153], v[182:185], v[134:137]
	v_mfma_f32_16x16x32_bf16 v[130:133], v[154:157], v[178:181], v[130:133]
	v_mfma_f32_16x16x32_bf16 v[130:133], v[158:161], v[182:185], v[130:133]
	v_mfma_f32_16x16x32_bf16 v[118:121], v[146:149], v[192:195], v[118:121]
	v_mfma_f32_16x16x32_bf16 v[118:121], v[150:153], v[196:199], v[118:121]
	v_mfma_f32_16x16x32_bf16 v[114:117], v[154:157], v[192:195], v[114:117]
	v_mfma_f32_16x16x32_bf16 v[114:117], v[158:161], v[196:199], v[114:117]
	v_mfma_f32_16x16x32_bf16 v[86:89], v[146:149], v[200:203], v[86:89]
	v_mfma_f32_16x16x32_bf16 v[86:89], v[150:153], v[204:207], v[86:89]
	v_mfma_f32_16x16x32_bf16 v[82:85], v[154:157], v[200:203], v[82:85]
	v_mfma_f32_16x16x32_bf16 v[82:85], v[158:161], v[204:207], v[82:85]
	v_mfma_f32_16x16x32_bf16 v[70:73], v[146:149], v[208:211], v[70:73]
	v_mfma_f32_16x16x32_bf16 v[70:73], v[150:153], v[212:215], v[70:73]
	v_mfma_f32_16x16x32_bf16 v[66:69], v[154:157], v[208:211], v[66:69]
	v_mfma_f32_16x16x32_bf16 v[66:69], v[158:161], v[212:215], v[66:69]
	s_setprio 0
	s_barrier
	s_add_i32 s52, s45, s33
	s_mov_b32 m0, s52
	ds_read_b128 v[178:181], v190 offset:16384
	ds_read_b128 v[182:185], v190 offset:17408
	ds_read_b128 v[192:195], v190 offset:18432
	ds_read_b128 v[196:199], v190 offset:19456
	ds_read_b128 v[200:203], v190 offset:20480
	ds_read_b128 v[204:207], v190 offset:21504
	ds_read_b128 v[208:211], v190 offset:22528
	ds_read_b128 v[212:215], v190 offset:23552
	global_load_lds_dwordx4 v164, s[30:31]
	s_add_i32 m0, s52, 0x2000
	s_add_u32 s52, s30, 0x100000
	s_addc_u32 s53, s31, 0
	s_add_i32 s54, s46, s33
	global_load_lds_dwordx4 v168, s[30:31]
	s_mov_b32 m0, s54
	global_load_lds_dwordx4 v164, s[52:53]
	s_add_i32 m0, s54, 0x2000
	s_nop 0
	global_load_lds_dwordx4 v168, s[52:53]
	s_mov_b32 m0, s36
	s_nop 0
	global_load_lds_dwordx4 v162, s[34:35]
	s_mov_b32 m0, s37
	s_nop 0
	global_load_lds_dwordx4 v166, s[34:35]
	s_waitcnt vmcnt(8)
	s_waitcnt lgkmcnt(0)
	s_barrier
	s_setprio 1
	s_waitcnt lgkmcnt(0)
	v_mfma_f32_16x16x32_bf16 v[62:65], v[90:93], v[178:181], v[62:65]
	v_mfma_f32_16x16x32_bf16 v[62:65], v[94:97], v[182:185], v[62:65]
	v_mfma_f32_16x16x32_bf16 v[58:61], v[102:105], v[178:181], v[58:61]
	v_mfma_f32_16x16x32_bf16 v[58:61], v[110:113], v[182:185], v[58:61]
	v_mfma_f32_16x16x32_bf16 v[46:49], v[90:93], v[192:195], v[46:49]
	v_mfma_f32_16x16x32_bf16 v[46:49], v[94:97], v[196:199], v[46:49]
	v_mfma_f32_16x16x32_bf16 v[42:45], v[102:105], v[192:195], v[42:45]
	v_mfma_f32_16x16x32_bf16 v[42:45], v[110:113], v[196:199], v[42:45]
	v_mfma_f32_16x16x32_bf16 v[30:33], v[90:93], v[200:203], v[30:33]
	v_mfma_f32_16x16x32_bf16 v[30:33], v[94:97], v[204:207], v[30:33]
	v_mfma_f32_16x16x32_bf16 v[26:29], v[102:105], v[200:203], v[26:29]
	v_mfma_f32_16x16x32_bf16 v[26:29], v[110:113], v[204:207], v[26:29]
	v_mfma_f32_16x16x32_bf16 v[14:17], v[90:93], v[208:211], v[14:17]
	v_mfma_f32_16x16x32_bf16 v[14:17], v[94:97], v[212:215], v[14:17]
	v_mfma_f32_16x16x32_bf16 v[10:13], v[102:105], v[208:211], v[10:13]
	v_mfma_f32_16x16x32_bf16 v[10:13], v[110:113], v[212:215], v[10:13]
	s_setprio 0
	s_setprio 1
	v_mfma_f32_16x16x32_bf16 v[54:57], v[146:149], v[178:181], v[54:57]
	v_mfma_f32_16x16x32_bf16 v[54:57], v[150:153], v[182:185], v[54:57]
	v_mfma_f32_16x16x32_bf16 v[50:53], v[154:157], v[178:181], v[50:53]
	v_mfma_f32_16x16x32_bf16 v[50:53], v[158:161], v[182:185], v[50:53]
	v_mfma_f32_16x16x32_bf16 v[38:41], v[146:149], v[192:195], v[38:41]
	v_mfma_f32_16x16x32_bf16 v[38:41], v[150:153], v[196:199], v[38:41]
	v_mfma_f32_16x16x32_bf16 v[34:37], v[154:157], v[192:195], v[34:37]
	v_mfma_f32_16x16x32_bf16 v[34:37], v[158:161], v[196:199], v[34:37]
	v_mfma_f32_16x16x32_bf16 v[22:25], v[146:149], v[200:203], v[22:25]
	v_mfma_f32_16x16x32_bf16 v[22:25], v[150:153], v[204:207], v[22:25]
	v_mfma_f32_16x16x32_bf16 v[18:21], v[154:157], v[200:203], v[18:21]
	v_mfma_f32_16x16x32_bf16 v[18:21], v[158:161], v[204:207], v[18:21]
	v_mfma_f32_16x16x32_bf16 v[6:9], v[146:149], v[208:211], v[6:9]
	v_mfma_f32_16x16x32_bf16 v[6:9], v[150:153], v[212:215], v[6:9]
	v_mfma_f32_16x16x32_bf16 v[2:5], v[154:157], v[208:211], v[2:5]
	v_mfma_f32_16x16x32_bf16 v[2:5], v[158:161], v[212:215], v[2:5]
	s_setprio 0
	s_barrier
	s_add_i32 s52, 0, 0x18000
	s_add_i32 s53, 0, 0x1c000
	v_add_u32_e32 v110, s52, v186
	v_add_u32_e32 v158, s53, v186
	ds_read_b128 v[90:93], v110
	ds_read_b128 v[94:97], v110 offset:1024
	ds_read_b128 v[102:105], v110 offset:2048
	ds_read_b128 v[110:113], v110 offset:3072
	ds_read_b128 v[146:149], v158
	ds_read_b128 v[150:153], v158 offset:1024
	ds_read_b128 v[154:157], v158 offset:2048
	ds_read_b128 v[158:161], v158 offset:3072
	s_add_u32 s98, s34, 0x80
	s_addc_u32 s99, s35, 0
	s_add_u32 s34, s34, 0x100000
	s_addc_u32 s35, s35, 0
	s_mov_b32 m0, s38
	ds_read_b128 v[178:181], v190 offset:32768
	ds_read_b128 v[182:185], v190 offset:33792
	ds_read_b128 v[192:195], v190 offset:34816
	ds_read_b128 v[196:199], v190 offset:35840
	ds_read_b128 v[200:203], v190 offset:36864
	ds_read_b128 v[204:207], v190 offset:37888
	ds_read_b128 v[208:211], v190 offset:38912
	ds_read_b128 v[212:215], v190 offset:39936
	global_load_lds_dwordx4 v162, s[34:35]
	s_mov_b32 m0, s39
	s_nop 0
	global_load_lds_dwordx4 v166, s[34:35]
	s_waitcnt vmcnt(8)
	s_waitcnt lgkmcnt(0)
	s_barrier
	s_setprio 1
	s_waitcnt lgkmcnt(0)
	v_mfma_f32_16x16x32_bf16 v[142:145], v[90:93], v[178:181], v[142:145]
	v_mfma_f32_16x16x32_bf16 v[142:145], v[94:97], v[182:185], v[142:145]
	v_mfma_f32_16x16x32_bf16 v[138:141], v[102:105], v[178:181], v[138:141]
	v_mfma_f32_16x16x32_bf16 v[138:141], v[110:113], v[182:185], v[138:141]
	v_mfma_f32_16x16x32_bf16 v[126:129], v[90:93], v[192:195], v[126:129]
	v_mfma_f32_16x16x32_bf16 v[126:129], v[94:97], v[196:199], v[126:129]
	v_mfma_f32_16x16x32_bf16 v[122:125], v[102:105], v[192:195], v[122:125]
	v_mfma_f32_16x16x32_bf16 v[122:125], v[110:113], v[196:199], v[122:125]
	v_mfma_f32_16x16x32_bf16 v[106:109], v[90:93], v[200:203], v[106:109]
	v_mfma_f32_16x16x32_bf16 v[106:109], v[94:97], v[204:207], v[106:109]
	v_mfma_f32_16x16x32_bf16 v[98:101], v[102:105], v[200:203], v[98:101]
	v_mfma_f32_16x16x32_bf16 v[98:101], v[110:113], v[204:207], v[98:101]
	v_mfma_f32_16x16x32_bf16 v[78:81], v[90:93], v[208:211], v[78:81]
	v_mfma_f32_16x16x32_bf16 v[78:81], v[94:97], v[212:215], v[78:81]
	v_mfma_f32_16x16x32_bf16 v[74:77], v[102:105], v[208:211], v[74:77]
	v_mfma_f32_16x16x32_bf16 v[74:77], v[110:113], v[212:215], v[74:77]
	s_setprio 0
	s_setprio 1
	v_mfma_f32_16x16x32_bf16 v[134:137], v[146:149], v[178:181], v[134:137]
	v_mfma_f32_16x16x32_bf16 v[134:137], v[150:153], v[182:185], v[134:137]
	v_mfma_f32_16x16x32_bf16 v[130:133], v[154:157], v[178:181], v[130:133]
	v_mfma_f32_16x16x32_bf16 v[130:133], v[158:161], v[182:185], v[130:133]
	v_mfma_f32_16x16x32_bf16 v[118:121], v[146:149], v[192:195], v[118:121]
	v_mfma_f32_16x16x32_bf16 v[118:121], v[150:153], v[196:199], v[118:121]
	v_mfma_f32_16x16x32_bf16 v[114:117], v[154:157], v[192:195], v[114:117]
	v_mfma_f32_16x16x32_bf16 v[114:117], v[158:161], v[196:199], v[114:117]
	v_mfma_f32_16x16x32_bf16 v[86:89], v[146:149], v[200:203], v[86:89]
	v_mfma_f32_16x16x32_bf16 v[86:89], v[150:153], v[204:207], v[86:89]
	v_mfma_f32_16x16x32_bf16 v[82:85], v[154:157], v[200:203], v[82:85]
	v_mfma_f32_16x16x32_bf16 v[82:85], v[158:161], v[204:207], v[82:85]
	v_mfma_f32_16x16x32_bf16 v[70:73], v[146:149], v[208:211], v[70:73]
	v_mfma_f32_16x16x32_bf16 v[70:73], v[150:153], v[212:215], v[70:73]
	v_mfma_f32_16x16x32_bf16 v[66:69], v[154:157], v[208:211], v[66:69]
	v_mfma_f32_16x16x32_bf16 v[66:69], v[158:161], v[212:215], v[66:69]
	s_setprio 0
	s_barrier
	s_add_i32 s34, s52, s33
	s_mov_b32 m0, s34
	ds_read_b128 v[178:181], v190 offset:49152
	ds_read_b128 v[182:185], v190 offset:50176
	ds_read_b128 v[192:195], v190 offset:51200
	ds_read_b128 v[196:199], v190 offset:52224
	ds_read_b128 v[200:203], v190 offset:53248
	ds_read_b128 v[204:207], v190 offset:54272
	ds_read_b128 v[208:211], v190 offset:55296
	ds_read_b128 v[212:215], v190 offset:56320
	s_add_u32 s30, s30, 0x80
	s_addc_u32 s31, s31, 0
	global_load_lds_dwordx4 v164, s[30:31]
	s_add_i32 m0, s34, 0x2000
	s_add_i32 s34, s53, s33
	global_load_lds_dwordx4 v168, s[30:31]
	s_add_u32 s30, s30, 0x100000
	s_addc_u32 s31, s31, 0
	s_mov_b32 m0, s34
	s_nop 0
	global_load_lds_dwordx4 v164, s[30:31]
	s_add_i32 m0, s34, 0x2000
	s_nop 0
	global_load_lds_dwordx4 v168, s[30:31]
	s_mov_b32 m0, s43
	s_nop 0
	global_load_lds_dwordx4 v162, s[98:99]
	s_mov_b32 m0, s44
	s_nop 0
	global_load_lds_dwordx4 v166, s[98:99]
	s_waitcnt vmcnt(8)
	s_waitcnt lgkmcnt(0)
	s_barrier
	s_setprio 1
	s_waitcnt lgkmcnt(0)
	v_mfma_f32_16x16x32_bf16 v[62:65], v[90:93], v[178:181], v[62:65]
	v_mfma_f32_16x16x32_bf16 v[62:65], v[94:97], v[182:185], v[62:65]
	v_mfma_f32_16x16x32_bf16 v[58:61], v[102:105], v[178:181], v[58:61]
	v_mfma_f32_16x16x32_bf16 v[58:61], v[110:113], v[182:185], v[58:61]
	v_mfma_f32_16x16x32_bf16 v[46:49], v[90:93], v[192:195], v[46:49]
	v_mfma_f32_16x16x32_bf16 v[46:49], v[94:97], v[196:199], v[46:49]
	v_mfma_f32_16x16x32_bf16 v[42:45], v[102:105], v[192:195], v[42:45]
	v_mfma_f32_16x16x32_bf16 v[42:45], v[110:113], v[196:199], v[42:45]
	v_mfma_f32_16x16x32_bf16 v[30:33], v[90:93], v[200:203], v[30:33]
	v_mfma_f32_16x16x32_bf16 v[30:33], v[94:97], v[204:207], v[30:33]
	v_mfma_f32_16x16x32_bf16 v[26:29], v[102:105], v[200:203], v[26:29]
	v_mfma_f32_16x16x32_bf16 v[26:29], v[110:113], v[204:207], v[26:29]
	v_mfma_f32_16x16x32_bf16 v[14:17], v[90:93], v[208:211], v[14:17]
	v_mfma_f32_16x16x32_bf16 v[14:17], v[94:97], v[212:215], v[14:17]
	v_mfma_f32_16x16x32_bf16 v[10:13], v[102:105], v[208:211], v[10:13]
	v_mfma_f32_16x16x32_bf16 v[10:13], v[110:113], v[212:215], v[10:13]
	s_setprio 0
	s_setprio 1
	v_mfma_f32_16x16x32_bf16 v[54:57], v[146:149], v[178:181], v[54:57]
	v_mfma_f32_16x16x32_bf16 v[54:57], v[150:153], v[182:185], v[54:57]
	v_mfma_f32_16x16x32_bf16 v[50:53], v[154:157], v[178:181], v[50:53]
	v_mfma_f32_16x16x32_bf16 v[50:53], v[158:161], v[182:185], v[50:53]
	v_mfma_f32_16x16x32_bf16 v[38:41], v[146:149], v[192:195], v[38:41]
	v_mfma_f32_16x16x32_bf16 v[38:41], v[150:153], v[196:199], v[38:41]
	v_mfma_f32_16x16x32_bf16 v[34:37], v[154:157], v[192:195], v[34:37]
	v_mfma_f32_16x16x32_bf16 v[34:37], v[158:161], v[196:199], v[34:37]
	v_mfma_f32_16x16x32_bf16 v[22:25], v[146:149], v[200:203], v[22:25]
	v_mfma_f32_16x16x32_bf16 v[22:25], v[150:153], v[204:207], v[22:25]
	v_mfma_f32_16x16x32_bf16 v[18:21], v[154:157], v[200:203], v[18:21]
	v_mfma_f32_16x16x32_bf16 v[18:21], v[158:161], v[204:207], v[18:21]
	v_mfma_f32_16x16x32_bf16 v[6:9], v[146:149], v[208:211], v[6:9]
	v_mfma_f32_16x16x32_bf16 v[6:9], v[150:153], v[212:215], v[6:9]
	v_mfma_f32_16x16x32_bf16 v[2:5], v[154:157], v[208:211], v[2:5]
	v_mfma_f32_16x16x32_bf16 v[2:5], v[158:161], v[212:215], v[2:5]
	s_setprio 0
	s_barrier
	s_add_i32 s51, s51, 2
	s_add_u32 s28, s28, 0x100
	s_addc_u32 s29, s29, 0
	s_add_u32 s49, s49, 0x100
	s_addc_u32 s50, s50, 0
	s_cmp_gt_u32 s51, 61
	s_cbranch_scc0 .LBB0_941
	s_and_b64 vcc, exec, s[16:17]
	s_cbranch_vccz .LBB0_944
	s_barrier

.LBB0_1153:
	v_add_u32_e32 v146, s78, v187
	v_add_u32_e32 v162, s79, v187
	s_add_u32 s98, s46, s10
	s_addc_u32 s99, s47, s11
	s_add_u32 s98, s98, 0x100080
	s_addc_u32 s99, s99, 0
	s_add_u32 s56, s46, s10
	ds_read_b128 v[134:137], v146
	ds_read_b128 v[138:141], v146 offset:1024
	ds_read_b128 v[142:145], v146 offset:2048
	ds_read_b128 v[146:149], v146 offset:3072
	ds_read_b128 v[150:153], v162
	ds_read_b128 v[154:157], v162 offset:1024
	ds_read_b128 v[158:161], v162 offset:2048
	ds_read_b128 v[162:165], v162 offset:3072
	s_addc_u32 s57, s47, s11
	s_add_u32 s56, s56, 0x100
	s_addc_u32 s57, s57, 0
	s_add_u32 s84, s33, s10
	s_addc_u32 s85, s72, s11
	s_cmpk_eq_i32 s10, 0x1f00
	s_cselect_b32 s59, s29, s57
	s_cselect_b32 s58, s45, s56
	s_cselect_b32 s57, s43, s85
	s_cselect_b32 s56, s73, s84
	s_add_i32 m0, s64, 0xc000
	ds_read_b128 v[166:169], v230
	ds_read_b128 v[170:173], v230 offset:1024
	ds_read_b128 v[174:177], v230 offset:2048
	ds_read_b128 v[202:205], v230 offset:3072
	ds_read_b128 v[206:209], v230 offset:4096
	ds_read_b128 v[210:213], v230 offset:5120
	ds_read_b128 v[214:217], v230 offset:6144
	ds_read_b128 v[218:221], v230 offset:7168
	global_load_lds_dwordx4 v178, s[98:99]
	s_add_i32 m0, s64, 0xe000
	s_nop 0
	global_load_lds_dwordx4 v182, s[98:99]
	s_waitcnt vmcnt(8)
	s_waitcnt lgkmcnt(0)
	s_barrier
	s_setprio 1
	s_waitcnt lgkmcnt(0)
	v_mfma_f32_16x16x32_bf16 v[2:5], v[134:137], v[166:169], v[2:5]
	v_mfma_f32_16x16x32_bf16 v[2:5], v[138:141], v[170:173], v[2:5]
	v_mfma_f32_16x16x32_bf16 v[126:129], v[142:145], v[166:169], v[126:129]
	v_mfma_f32_16x16x32_bf16 v[126:129], v[146:149], v[170:173], v[126:129]
	v_mfma_f32_16x16x32_bf16 v[122:125], v[134:137], v[174:177], v[122:125]
	v_mfma_f32_16x16x32_bf16 v[122:125], v[138:141], v[202:205], v[122:125]
	v_mfma_f32_16x16x32_bf16 v[118:121], v[142:145], v[174:177], v[118:121]
	v_mfma_f32_16x16x32_bf16 v[118:121], v[146:149], v[202:205], v[118:121]
	v_mfma_f32_16x16x32_bf16 v[114:117], v[134:137], v[206:209], v[114:117]
	v_mfma_f32_16x16x32_bf16 v[114:117], v[138:141], v[210:213], v[114:117]
	v_mfma_f32_16x16x32_bf16 v[110:113], v[142:145], v[206:209], v[110:113]
	v_mfma_f32_16x16x32_bf16 v[110:113], v[146:149], v[210:213], v[110:113]
	v_mfma_f32_16x16x32_bf16 v[106:109], v[134:137], v[214:217], v[106:109]
	v_mfma_f32_16x16x32_bf16 v[106:109], v[138:141], v[218:221], v[106:109]
	v_mfma_f32_16x16x32_bf16 v[102:105], v[142:145], v[214:217], v[102:105]
	v_mfma_f32_16x16x32_bf16 v[102:105], v[146:149], v[218:221], v[102:105]
	s_setprio 0
	s_setprio 1
	v_mfma_f32_16x16x32_bf16 v[98:101], v[150:153], v[166:169], v[98:101]
	v_mfma_f32_16x16x32_bf16 v[98:101], v[154:157], v[170:173], v[98:101]
	v_mfma_f32_16x16x32_bf16 v[94:97], v[158:161], v[166:169], v[94:97]
	v_mfma_f32_16x16x32_bf16 v[94:97], v[162:165], v[170:173], v[94:97]
	v_mfma_f32_16x16x32_bf16 v[90:93], v[150:153], v[174:177], v[90:93]
	v_mfma_f32_16x16x32_bf16 v[90:93], v[154:157], v[202:205], v[90:93]
	v_mfma_f32_16x16x32_bf16 v[86:89], v[158:161], v[174:177], v[86:89]
	v_mfma_f32_16x16x32_bf16 v[86:89], v[162:165], v[202:205], v[86:89]
	v_mfma_f32_16x16x32_bf16 v[82:85], v[150:153], v[206:209], v[82:85]
	v_mfma_f32_16x16x32_bf16 v[82:85], v[154:157], v[210:213], v[82:85]
	v_mfma_f32_16x16x32_bf16 v[78:81], v[158:161], v[206:209], v[78:81]
	v_mfma_f32_16x16x32_bf16 v[78:81], v[162:165], v[210:213], v[78:81]
	v_mfma_f32_16x16x32_bf16 v[74:77], v[150:153], v[214:217], v[74:77]
	v_mfma_f32_16x16x32_bf16 v[74:77], v[154:157], v[218:221], v[74:77]
	v_mfma_f32_16x16x32_bf16 v[70:73], v[158:161], v[214:217], v[70:73]
	v_mfma_f32_16x16x32_bf16 v[70:73], v[162:165], v[218:221], v[70:73]
	s_setprio 0
	s_barrier
	s_add_i32 s84, s78, s63
	s_mov_b32 m0, s84
	ds_read_b128 v[166:169], v230 offset:16384
	ds_read_b128 v[170:173], v230 offset:17408
	ds_read_b128 v[174:177], v230 offset:18432
	ds_read_b128 v[202:205], v230 offset:19456
	ds_read_b128 v[206:209], v230 offset:20480
	ds_read_b128 v[210:213], v230 offset:21504
	ds_read_b128 v[214:217], v230 offset:22528
	ds_read_b128 v[218:221], v230 offset:23552
	global_load_lds_dwordx4 v180, s[56:57]
	s_add_i32 m0, s84, 0x2000
	s_add_u32 s84, s56, 0x100000
	s_addc_u32 s85, s57, 0
	s_add_i32 s86, s79, s63
	global_load_lds_dwordx4 v184, s[56:57]
	s_mov_b32 m0, s86
	s_nop 0
	global_load_lds_dwordx4 v180, s[84:85]
	s_add_i32 m0, s86, 0x2000
	s_nop 0
	global_load_lds_dwordx4 v184, s[84:85]
	s_mov_b32 m0, s64
	s_nop 0
	global_load_lds_dwordx4 v178, s[58:59]
	s_mov_b32 m0, s65
	s_nop 0
	global_load_lds_dwordx4 v182, s[58:59]
	s_waitcnt vmcnt(8)
	s_waitcnt lgkmcnt(0)
	s_barrier
	s_setprio 1
	s_waitcnt lgkmcnt(0)
	v_mfma_f32_16x16x32_bf16 v[66:69], v[134:137], v[166:169], v[66:69]
	v_mfma_f32_16x16x32_bf16 v[66:69], v[138:141], v[170:173], v[66:69]
	v_mfma_f32_16x16x32_bf16 v[62:65], v[142:145], v[166:169], v[62:65]
	v_mfma_f32_16x16x32_bf16 v[62:65], v[146:149], v[170:173], v[62:65]
	v_mfma_f32_16x16x32_bf16 v[58:61], v[134:137], v[174:177], v[58:61]
	v_mfma_f32_16x16x32_bf16 v[58:61], v[138:141], v[202:205], v[58:61]
	v_mfma_f32_16x16x32_bf16 v[54:57], v[142:145], v[174:177], v[54:57]
	v_mfma_f32_16x16x32_bf16 v[54:57], v[146:149], v[202:205], v[54:57]
	v_mfma_f32_16x16x32_bf16 v[50:53], v[134:137], v[206:209], v[50:53]
	v_mfma_f32_16x16x32_bf16 v[50:53], v[138:141], v[210:213], v[50:53]
	v_mfma_f32_16x16x32_bf16 v[46:49], v[142:145], v[206:209], v[46:49]
	v_mfma_f32_16x16x32_bf16 v[46:49], v[146:149], v[210:213], v[46:49]
	v_mfma_f32_16x16x32_bf16 v[42:45], v[134:137], v[214:217], v[42:45]
	v_mfma_f32_16x16x32_bf16 v[42:45], v[138:141], v[218:221], v[42:45]
	v_mfma_f32_16x16x32_bf16 v[38:41], v[142:145], v[214:217], v[38:41]
	v_mfma_f32_16x16x32_bf16 v[38:41], v[146:149], v[218:221], v[38:41]
	s_setprio 0
	s_setprio 1
	v_mfma_f32_16x16x32_bf16 v[34:37], v[150:153], v[166:169], v[34:37]
	v_mfma_f32_16x16x32_bf16 v[34:37], v[154:157], v[170:173], v[34:37]
	v_mfma_f32_16x16x32_bf16 v[30:33], v[158:161], v[166:169], v[30:33]
	v_mfma_f32_16x16x32_bf16 v[30:33], v[162:165], v[170:173], v[30:33]
	v_mfma_f32_16x16x32_bf16 v[26:29], v[150:153], v[174:177], v[26:29]
	v_mfma_f32_16x16x32_bf16 v[26:29], v[154:157], v[202:205], v[26:29]
	v_mfma_f32_16x16x32_bf16 v[22:25], v[158:161], v[174:177], v[22:25]
	v_mfma_f32_16x16x32_bf16 v[22:25], v[162:165], v[202:205], v[22:25]
	v_mfma_f32_16x16x32_bf16 v[18:21], v[150:153], v[206:209], v[18:21]
	v_mfma_f32_16x16x32_bf16 v[18:21], v[154:157], v[210:213], v[18:21]
	v_mfma_f32_16x16x32_bf16 v[14:17], v[158:161], v[206:209], v[14:17]
	v_mfma_f32_16x16x32_bf16 v[14:17], v[162:165], v[210:213], v[14:17]
	v_mfma_f32_16x16x32_bf16 v[10:13], v[150:153], v[214:217], v[10:13]
	v_mfma_f32_16x16x32_bf16 v[10:13], v[154:157], v[218:221], v[10:13]
	v_mfma_f32_16x16x32_bf16 v[6:9], v[158:161], v[214:217], v[6:9]
	v_mfma_f32_16x16x32_bf16 v[6:9], v[162:165], v[218:221], v[6:9]
	s_setprio 0
	s_barrier
	s_add_i32 s84, 0, 0x18000
	s_add_i32 s85, 0, 0x1c000
	v_add_u32_e32 v146, s84, v187
	v_add_u32_e32 v162, s85, v187
	ds_read_b128 v[134:137], v146
	ds_read_b128 v[138:141], v146 offset:1024
	ds_read_b128 v[142:145], v146 offset:2048
	ds_read_b128 v[146:149], v146 offset:3072
	ds_read_b128 v[150:153], v162
	ds_read_b128 v[154:157], v162 offset:1024
	ds_read_b128 v[158:161], v162 offset:2048
	ds_read_b128 v[162:165], v162 offset:3072
	s_add_u32 s100, s58, 0x80
	s_addc_u32 s101, s59, 0
	s_add_u32 s58, s58, 0x100000
	s_addc_u32 s59, s59, 0
	s_mov_b32 m0, s67
	ds_read_b128 v[166:169], v230 offset:32768
	ds_read_b128 v[170:173], v230 offset:33792
	ds_read_b128 v[174:177], v230 offset:34816
	ds_read_b128 v[202:205], v230 offset:35840
	ds_read_b128 v[206:209], v230 offset:36864
	ds_read_b128 v[210:213], v230 offset:37888
	ds_read_b128 v[214:217], v230 offset:38912
	ds_read_b128 v[218:221], v230 offset:39936
	global_load_lds_dwordx4 v178, s[58:59]
	s_mov_b32 m0, s68
	s_nop 0
	global_load_lds_dwordx4 v182, s[58:59]
	s_waitcnt vmcnt(8)
	s_waitcnt lgkmcnt(0)
	s_barrier
	s_setprio 1
	s_waitcnt lgkmcnt(0)
	v_mfma_f32_16x16x32_bf16 v[2:5], v[134:137], v[166:169], v[2:5]
	v_mfma_f32_16x16x32_bf16 v[2:5], v[138:141], v[170:173], v[2:5]
	v_mfma_f32_16x16x32_bf16 v[126:129], v[142:145], v[166:169], v[126:129]
	v_mfma_f32_16x16x32_bf16 v[126:129], v[146:149], v[170:173], v[126:129]
	v_mfma_f32_16x16x32_bf16 v[122:125], v[134:137], v[174:177], v[122:125]
	v_mfma_f32_16x16x32_bf16 v[122:125], v[138:141], v[202:205], v[122:125]
	v_mfma_f32_16x16x32_bf16 v[118:121], v[142:145], v[174:177], v[118:121]
	v_mfma_f32_16x16x32_bf16 v[118:121], v[146:149], v[202:205], v[118:121]
	v_mfma_f32_16x16x32_bf16 v[114:117], v[134:137], v[206:209], v[114:117]
	v_mfma_f32_16x16x32_bf16 v[114:117], v[138:141], v[210:213], v[114:117]
	v_mfma_f32_16x16x32_bf16 v[110:113], v[142:145], v[206:209], v[110:113]
	v_mfma_f32_16x16x32_bf16 v[110:113], v[146:149], v[210:213], v[110:113]
	v_mfma_f32_16x16x32_bf16 v[106:109], v[134:137], v[214:217], v[106:109]
	v_mfma_f32_16x16x32_bf16 v[106:109], v[138:141], v[218:221], v[106:109]
	v_mfma_f32_16x16x32_bf16 v[102:105], v[142:145], v[214:217], v[102:105]
	v_mfma_f32_16x16x32_bf16 v[102:105], v[146:149], v[218:221], v[102:105]
	s_setprio 0
	s_setprio 1
	v_mfma_f32_16x16x32_bf16 v[98:101], v[150:153], v[166:169], v[98:101]
	v_mfma_f32_16x16x32_bf16 v[98:101], v[154:157], v[170:173], v[98:101]
	v_mfma_f32_16x16x32_bf16 v[94:97], v[158:161], v[166:169], v[94:97]
	v_mfma_f32_16x16x32_bf16 v[94:97], v[162:165], v[170:173], v[94:97]
	v_mfma_f32_16x16x32_bf16 v[90:93], v[150:153], v[174:177], v[90:93]
	v_mfma_f32_16x16x32_bf16 v[90:93], v[154:157], v[202:205], v[90:93]
	v_mfma_f32_16x16x32_bf16 v[86:89], v[158:161], v[174:177], v[86:89]
	v_mfma_f32_16x16x32_bf16 v[86:89], v[162:165], v[202:205], v[86:89]
	v_mfma_f32_16x16x32_bf16 v[82:85], v[150:153], v[206:209], v[82:85]
	v_mfma_f32_16x16x32_bf16 v[82:85], v[154:157], v[210:213], v[82:85]
	v_mfma_f32_16x16x32_bf16 v[78:81], v[158:161], v[206:209], v[78:81]
	v_mfma_f32_16x16x32_bf16 v[78:81], v[162:165], v[210:213], v[78:81]
	v_mfma_f32_16x16x32_bf16 v[74:77], v[150:153], v[214:217], v[74:77]
	v_mfma_f32_16x16x32_bf16 v[74:77], v[154:157], v[218:221], v[74:77]
	v_mfma_f32_16x16x32_bf16 v[70:73], v[158:161], v[214:217], v[70:73]
	v_mfma_f32_16x16x32_bf16 v[70:73], v[162:165], v[218:221], v[70:73]
	s_setprio 0
	s_barrier
	s_add_i32 s58, s84, s63
	s_add_u32 s98, s56, 0x80
	s_addc_u32 s99, s57, 0
	s_mov_b32 m0, s58
	ds_read_b128 v[166:169], v230 offset:49152
	ds_read_b128 v[170:173], v230 offset:50176
	ds_read_b128 v[174:177], v230 offset:51200
	ds_read_b128 v[202:205], v230 offset:52224
	ds_read_b128 v[206:209], v230 offset:53248
	ds_read_b128 v[210:213], v230 offset:54272
	ds_read_b128 v[214:217], v230 offset:55296
	ds_read_b128 v[218:221], v230 offset:56320
	global_load_lds_dwordx4 v180, s[98:99]
	s_add_i32 m0, s58, 0x2000
	s_add_u32 s56, s56, 0x100080
	s_addc_u32 s57, s57, 0
	s_add_i32 s58, s85, s63
	global_load_lds_dwordx4 v184, s[98:99]
	s_mov_b32 m0, s58
	s_nop 0
	global_load_lds_dwordx4 v180, s[56:57]
	s_add_i32 m0, s58, 0x2000
	s_nop 0
	global_load_lds_dwordx4 v184, s[56:57]
	s_mov_b32 m0, s74
	s_nop 0
	global_load_lds_dwordx4 v178, s[100:101]
	s_mov_b32 m0, s75
	s_nop 0
	global_load_lds_dwordx4 v182, s[100:101]
	s_waitcnt vmcnt(8)
	s_waitcnt lgkmcnt(0)
	s_barrier
	s_setprio 1
	s_waitcnt lgkmcnt(0)
	v_mfma_f32_16x16x32_bf16 v[66:69], v[134:137], v[166:169], v[66:69]
	v_mfma_f32_16x16x32_bf16 v[66:69], v[138:141], v[170:173], v[66:69]
	v_mfma_f32_16x16x32_bf16 v[62:65], v[142:145], v[166:169], v[62:65]
	v_mfma_f32_16x16x32_bf16 v[62:65], v[146:149], v[170:173], v[62:65]
	v_mfma_f32_16x16x32_bf16 v[58:61], v[134:137], v[174:177], v[58:61]
	v_mfma_f32_16x16x32_bf16 v[58:61], v[138:141], v[202:205], v[58:61]
	v_mfma_f32_16x16x32_bf16 v[54:57], v[142:145], v[174:177], v[54:57]
	v_mfma_f32_16x16x32_bf16 v[54:57], v[146:149], v[202:205], v[54:57]
	v_mfma_f32_16x16x32_bf16 v[50:53], v[134:137], v[206:209], v[50:53]
	v_mfma_f32_16x16x32_bf16 v[50:53], v[138:141], v[210:213], v[50:53]
	v_mfma_f32_16x16x32_bf16 v[46:49], v[142:145], v[206:209], v[46:49]
	v_mfma_f32_16x16x32_bf16 v[46:49], v[146:149], v[210:213], v[46:49]
	v_mfma_f32_16x16x32_bf16 v[42:45], v[134:137], v[214:217], v[42:45]
	v_mfma_f32_16x16x32_bf16 v[42:45], v[138:141], v[218:221], v[42:45]
	v_mfma_f32_16x16x32_bf16 v[38:41], v[142:145], v[214:217], v[38:41]
	v_mfma_f32_16x16x32_bf16 v[38:41], v[146:149], v[218:221], v[38:41]
	s_setprio 0
	s_setprio 1
	v_mfma_f32_16x16x32_bf16 v[34:37], v[150:153], v[166:169], v[34:37]
	v_mfma_f32_16x16x32_bf16 v[34:37], v[154:157], v[170:173], v[34:37]
	v_mfma_f32_16x16x32_bf16 v[30:33], v[158:161], v[166:169], v[30:33]
	v_mfma_f32_16x16x32_bf16 v[30:33], v[162:165], v[170:173], v[30:33]
	v_mfma_f32_16x16x32_bf16 v[26:29], v[150:153], v[174:177], v[26:29]
	v_mfma_f32_16x16x32_bf16 v[26:29], v[154:157], v[202:205], v[26:29]
	v_mfma_f32_16x16x32_bf16 v[22:25], v[158:161], v[174:177], v[22:25]
	v_mfma_f32_16x16x32_bf16 v[22:25], v[162:165], v[202:205], v[22:25]
	v_mfma_f32_16x16x32_bf16 v[18:21], v[150:153], v[206:209], v[18:21]
	v_mfma_f32_16x16x32_bf16 v[18:21], v[154:157], v[210:213], v[18:21]
	v_mfma_f32_16x16x32_bf16 v[14:17], v[158:161], v[206:209], v[14:17]
	v_mfma_f32_16x16x32_bf16 v[14:17], v[162:165], v[210:213], v[14:17]
	v_mfma_f32_16x16x32_bf16 v[10:13], v[150:153], v[214:217], v[10:13]
	v_mfma_f32_16x16x32_bf16 v[10:13], v[154:157], v[218:221], v[10:13]
	v_mfma_f32_16x16x32_bf16 v[6:9], v[158:161], v[214:217], v[6:9]
	v_mfma_f32_16x16x32_bf16 v[6:9], v[162:165], v[218:221], v[6:9]
	s_setprio 0
	s_barrier
	s_add_i32 s83, s83, 2
	s_add_u32 s10, s10, 0x100
	s_addc_u32 s11, s11, 0
	s_cmp_gt_u32 s83, 61
	s_cbranch_scc0 .LBB0_1153
	s_and_b64 vcc, exec, s[36:37]
	s_cbranch_vccz .LBB0_1156
	s_barrier

.LBB0_1325:
	ds_read_b128 v[130:133], v176
	ds_read_b128 v[134:137], v176 offset:1024
	ds_read_b128 v[138:141], v176 offset:2048
	ds_read_b128 v[142:145], v176 offset:3072
	ds_read_b128 v[146:149], v177
	ds_read_b128 v[166:169], v177 offset:1024
	ds_read_b128 v[170:173], v177 offset:2048
	ds_read_b128 v[180:183], v177 offset:3072
	s_add_u32 s26, s24, 0xffd50080
	s_addc_u32 s27, s25, -1
	s_cmpk_eq_i32 s49, 0xa8
	s_cselect_b32 s29, s5, s27
	s_cselect_b32 s28, s4, s26
	s_cselect_b32 s27, s23, s48
	s_cselect_b32 s26, s22, s47
	s_add_i32 m0, s33, 0xc000
	ds_read_b128 v[184:187], v178
	ds_read_b128 v[188:191], v178 offset:1024
	ds_read_b128 v[192:195], v178 offset:2048
	ds_read_b128 v[196:199], v178 offset:3072
	ds_read_b128 v[200:203], v178 offset:4096
	ds_read_b128 v[204:207], v178 offset:5120
	ds_read_b128 v[208:211], v178 offset:6144
	ds_read_b128 v[212:215], v178 offset:7168
	global_load_lds_dwordx4 v158, s[24:25]
	s_add_i32 m0, s33, 0xe000
	s_nop 0
	global_load_lds_dwordx4 v160, s[24:25]
	s_waitcnt vmcnt(8)
	s_waitcnt lgkmcnt(0)
	s_barrier
	s_setprio 1
	s_waitcnt lgkmcnt(0)
	v_mfma_f32_16x16x32_bf16 v[126:129], v[130:133], v[184:187], v[126:129]
	v_mfma_f32_16x16x32_bf16 v[126:129], v[134:137], v[188:191], v[126:129]
	v_mfma_f32_16x16x32_bf16 v[122:125], v[138:141], v[184:187], v[122:125]
	v_mfma_f32_16x16x32_bf16 v[122:125], v[142:145], v[188:191], v[122:125]
	v_mfma_f32_16x16x32_bf16 v[110:113], v[130:133], v[192:195], v[110:113]
	v_mfma_f32_16x16x32_bf16 v[110:113], v[134:137], v[196:199], v[110:113]
	v_mfma_f32_16x16x32_bf16 v[106:109], v[138:141], v[192:195], v[106:109]
	v_mfma_f32_16x16x32_bf16 v[106:109], v[142:145], v[196:199], v[106:109]
	v_mfma_f32_16x16x32_bf16 v[94:97], v[130:133], v[200:203], v[94:97]
	v_mfma_f32_16x16x32_bf16 v[94:97], v[134:137], v[204:207], v[94:97]
	v_mfma_f32_16x16x32_bf16 v[90:93], v[138:141], v[200:203], v[90:93]
	v_mfma_f32_16x16x32_bf16 v[90:93], v[142:145], v[204:207], v[90:93]
	v_mfma_f32_16x16x32_bf16 v[78:81], v[130:133], v[208:211], v[78:81]
	v_mfma_f32_16x16x32_bf16 v[78:81], v[134:137], v[212:215], v[78:81]
	v_mfma_f32_16x16x32_bf16 v[74:77], v[138:141], v[208:211], v[74:77]
	v_mfma_f32_16x16x32_bf16 v[74:77], v[142:145], v[212:215], v[74:77]
	s_setprio 0
	s_setprio 1
	v_mfma_f32_16x16x32_bf16 v[118:121], v[146:149], v[184:187], v[118:121]
	v_mfma_f32_16x16x32_bf16 v[118:121], v[166:169], v[188:191], v[118:121]
	v_mfma_f32_16x16x32_bf16 v[114:117], v[170:173], v[184:187], v[114:117]
	v_mfma_f32_16x16x32_bf16 v[114:117], v[180:183], v[188:191], v[114:117]
	v_mfma_f32_16x16x32_bf16 v[102:105], v[146:149], v[192:195], v[102:105]
	v_mfma_f32_16x16x32_bf16 v[102:105], v[166:169], v[196:199], v[102:105]
	v_mfma_f32_16x16x32_bf16 v[98:101], v[170:173], v[192:195], v[98:101]
	v_mfma_f32_16x16x32_bf16 v[98:101], v[180:183], v[196:199], v[98:101]
	v_mfma_f32_16x16x32_bf16 v[86:89], v[146:149], v[200:203], v[86:89]
	v_mfma_f32_16x16x32_bf16 v[86:89], v[166:169], v[204:207], v[86:89]
	v_mfma_f32_16x16x32_bf16 v[82:85], v[170:173], v[200:203], v[82:85]
	v_mfma_f32_16x16x32_bf16 v[82:85], v[180:183], v[204:207], v[82:85]
	v_mfma_f32_16x16x32_bf16 v[70:73], v[146:149], v[208:211], v[70:73]
	v_mfma_f32_16x16x32_bf16 v[70:73], v[166:169], v[212:215], v[70:73]
	v_mfma_f32_16x16x32_bf16 v[66:69], v[170:173], v[208:211], v[66:69]
	v_mfma_f32_16x16x32_bf16 v[66:69], v[180:183], v[212:215], v[66:69]
	s_setprio 0
	s_barrier
	s_add_i32 s50, s41, s31
	s_mov_b32 m0, s50
	ds_read_b128 v[184:187], v178 offset:16384
	ds_read_b128 v[188:191], v178 offset:17408
	ds_read_b128 v[192:195], v178 offset:18432
	ds_read_b128 v[196:199], v178 offset:19456
	ds_read_b128 v[200:203], v178 offset:20480
	ds_read_b128 v[204:207], v178 offset:21504
	ds_read_b128 v[208:211], v178 offset:22528
	ds_read_b128 v[212:215], v178 offset:23552
	global_load_lds_dwordx4 v152, s[26:27]
	s_add_i32 m0, s50, 0x2000
	s_add_u32 s50, s26, 0x2b0000
	s_addc_u32 s51, s27, 0
	s_add_i32 s52, s42, s31
	global_load_lds_dwordx4 v156, s[26:27]
	s_mov_b32 m0, s52
	global_load_lds_dwordx4 v152, s[50:51]
	s_add_i32 m0, s52, 0x2000
	s_nop 0
	global_load_lds_dwordx4 v156, s[50:51]
	s_mov_b32 m0, s33
	s_nop 0
	global_load_lds_dwordx4 v150, s[28:29]
	s_mov_b32 m0, s34
	s_nop 0
	global_load_lds_dwordx4 v154, s[28:29]
	s_waitcnt vmcnt(8)
	s_waitcnt lgkmcnt(0)
	s_barrier
	s_setprio 1
	s_waitcnt lgkmcnt(0)
	v_mfma_f32_16x16x32_bf16 v[62:65], v[130:133], v[184:187], v[62:65]
	v_mfma_f32_16x16x32_bf16 v[62:65], v[134:137], v[188:191], v[62:65]
	v_mfma_f32_16x16x32_bf16 v[58:61], v[138:141], v[184:187], v[58:61]
	v_mfma_f32_16x16x32_bf16 v[58:61], v[142:145], v[188:191], v[58:61]
	v_mfma_f32_16x16x32_bf16 v[46:49], v[130:133], v[192:195], v[46:49]
	v_mfma_f32_16x16x32_bf16 v[46:49], v[134:137], v[196:199], v[46:49]
	v_mfma_f32_16x16x32_bf16 v[42:45], v[138:141], v[192:195], v[42:45]
	v_mfma_f32_16x16x32_bf16 v[42:45], v[142:145], v[196:199], v[42:45]
	v_mfma_f32_16x16x32_bf16 v[30:33], v[130:133], v[200:203], v[30:33]
	v_mfma_f32_16x16x32_bf16 v[30:33], v[134:137], v[204:207], v[30:33]
	v_mfma_f32_16x16x32_bf16 v[26:29], v[138:141], v[200:203], v[26:29]
	v_mfma_f32_16x16x32_bf16 v[26:29], v[142:145], v[204:207], v[26:29]
	v_mfma_f32_16x16x32_bf16 v[14:17], v[130:133], v[208:211], v[14:17]
	v_mfma_f32_16x16x32_bf16 v[14:17], v[134:137], v[212:215], v[14:17]
	v_mfma_f32_16x16x32_bf16 v[10:13], v[138:141], v[208:211], v[10:13]
	v_mfma_f32_16x16x32_bf16 v[10:13], v[142:145], v[212:215], v[10:13]
	s_setprio 0
	s_setprio 1
	v_mfma_f32_16x16x32_bf16 v[54:57], v[146:149], v[184:187], v[54:57]
	v_mfma_f32_16x16x32_bf16 v[54:57], v[166:169], v[188:191], v[54:57]
	v_mfma_f32_16x16x32_bf16 v[50:53], v[170:173], v[184:187], v[50:53]
	v_mfma_f32_16x16x32_bf16 v[50:53], v[180:183], v[188:191], v[50:53]
	v_mfma_f32_16x16x32_bf16 v[38:41], v[146:149], v[192:195], v[38:41]
	v_mfma_f32_16x16x32_bf16 v[38:41], v[166:169], v[196:199], v[38:41]
	v_mfma_f32_16x16x32_bf16 v[34:37], v[170:173], v[192:195], v[34:37]
	v_mfma_f32_16x16x32_bf16 v[34:37], v[180:183], v[196:199], v[34:37]
	v_mfma_f32_16x16x32_bf16 v[22:25], v[146:149], v[200:203], v[22:25]
	v_mfma_f32_16x16x32_bf16 v[22:25], v[166:169], v[204:207], v[22:25]
	v_mfma_f32_16x16x32_bf16 v[18:21], v[170:173], v[200:203], v[18:21]
	v_mfma_f32_16x16x32_bf16 v[18:21], v[180:183], v[204:207], v[18:21]
	v_mfma_f32_16x16x32_bf16 v[6:9], v[146:149], v[208:211], v[6:9]
	v_mfma_f32_16x16x32_bf16 v[6:9], v[166:169], v[212:215], v[6:9]
	v_mfma_f32_16x16x32_bf16 v[2:5], v[170:173], v[208:211], v[2:5]
	v_mfma_f32_16x16x32_bf16 v[2:5], v[180:183], v[212:215], v[2:5]
	s_setprio 0
	s_barrier
	s_add_i32 s50, 0, 0x18000
	s_add_i32 s51, 0, 0x1c000
	v_add_u32_e32 v142, s50, v174
	v_add_u32_e32 v179, s51, v174
	ds_read_b128 v[130:133], v142
	ds_read_b128 v[134:137], v142 offset:1024
	ds_read_b128 v[138:141], v142 offset:2048
	ds_read_b128 v[142:145], v142 offset:3072
	ds_read_b128 v[146:149], v179
	ds_read_b128 v[166:169], v179 offset:1024
	ds_read_b128 v[170:173], v179 offset:2048
	ds_read_b128 v[180:183], v179 offset:3072
	s_add_u32 s98, s28, 0x80
	s_addc_u32 s99, s29, 0
	s_add_u32 s28, s28, 0x2b0000
	s_addc_u32 s29, s29, 0
	s_mov_b32 m0, s35
	ds_read_b128 v[184:187], v178 offset:32768
	ds_read_b128 v[188:191], v178 offset:33792
	ds_read_b128 v[192:195], v178 offset:34816
	ds_read_b128 v[196:199], v178 offset:35840
	ds_read_b128 v[200:203], v178 offset:36864
	ds_read_b128 v[204:207], v178 offset:37888
	ds_read_b128 v[208:211], v178 offset:38912
	ds_read_b128 v[212:215], v178 offset:39936
	global_load_lds_dwordx4 v150, s[28:29]
	s_mov_b32 m0, s36
	s_nop 0
	global_load_lds_dwordx4 v154, s[28:29]
	s_waitcnt vmcnt(8)
	s_waitcnt lgkmcnt(0)
	s_barrier
	s_setprio 1
	s_waitcnt lgkmcnt(0)
	v_mfma_f32_16x16x32_bf16 v[126:129], v[130:133], v[184:187], v[126:129]
	v_mfma_f32_16x16x32_bf16 v[126:129], v[134:137], v[188:191], v[126:129]
	v_mfma_f32_16x16x32_bf16 v[122:125], v[138:141], v[184:187], v[122:125]
	v_mfma_f32_16x16x32_bf16 v[122:125], v[142:145], v[188:191], v[122:125]
	v_mfma_f32_16x16x32_bf16 v[110:113], v[130:133], v[192:195], v[110:113]
	v_mfma_f32_16x16x32_bf16 v[110:113], v[134:137], v[196:199], v[110:113]
	v_mfma_f32_16x16x32_bf16 v[106:109], v[138:141], v[192:195], v[106:109]
	v_mfma_f32_16x16x32_bf16 v[106:109], v[142:145], v[196:199], v[106:109]
	v_mfma_f32_16x16x32_bf16 v[94:97], v[130:133], v[200:203], v[94:97]
	v_mfma_f32_16x16x32_bf16 v[94:97], v[134:137], v[204:207], v[94:97]
	v_mfma_f32_16x16x32_bf16 v[90:93], v[138:141], v[200:203], v[90:93]
	v_mfma_f32_16x16x32_bf16 v[90:93], v[142:145], v[204:207], v[90:93]
	v_mfma_f32_16x16x32_bf16 v[78:81], v[130:133], v[208:211], v[78:81]
	v_mfma_f32_16x16x32_bf16 v[78:81], v[134:137], v[212:215], v[78:81]
	v_mfma_f32_16x16x32_bf16 v[74:77], v[138:141], v[208:211], v[74:77]
	v_mfma_f32_16x16x32_bf16 v[74:77], v[142:145], v[212:215], v[74:77]
	s_setprio 0
	s_setprio 1
	v_mfma_f32_16x16x32_bf16 v[118:121], v[146:149], v[184:187], v[118:121]
	v_mfma_f32_16x16x32_bf16 v[118:121], v[166:169], v[188:191], v[118:121]
	v_mfma_f32_16x16x32_bf16 v[114:117], v[170:173], v[184:187], v[114:117]
	v_mfma_f32_16x16x32_bf16 v[114:117], v[180:183], v[188:191], v[114:117]
	v_mfma_f32_16x16x32_bf16 v[102:105], v[146:149], v[192:195], v[102:105]
	v_mfma_f32_16x16x32_bf16 v[102:105], v[166:169], v[196:199], v[102:105]
	v_mfma_f32_16x16x32_bf16 v[98:101], v[170:173], v[192:195], v[98:101]
	v_mfma_f32_16x16x32_bf16 v[98:101], v[180:183], v[196:199], v[98:101]
	v_mfma_f32_16x16x32_bf16 v[86:89], v[146:149], v[200:203], v[86:89]
	v_mfma_f32_16x16x32_bf16 v[86:89], v[166:169], v[204:207], v[86:89]
	v_mfma_f32_16x16x32_bf16 v[82:85], v[170:173], v[200:203], v[82:85]
	v_mfma_f32_16x16x32_bf16 v[82:85], v[180:183], v[204:207], v[82:85]
	v_mfma_f32_16x16x32_bf16 v[70:73], v[146:149], v[208:211], v[70:73]
	v_mfma_f32_16x16x32_bf16 v[70:73], v[166:169], v[212:215], v[70:73]
	v_mfma_f32_16x16x32_bf16 v[66:69], v[170:173], v[208:211], v[66:69]
	v_mfma_f32_16x16x32_bf16 v[66:69], v[180:183], v[212:215], v[66:69]
	s_setprio 0
	s_barrier
	s_add_i32 s28, s50, s31
	s_mov_b32 m0, s28
	ds_read_b128 v[184:187], v178 offset:49152
	ds_read_b128 v[188:191], v178 offset:50176
	ds_read_b128 v[192:195], v178 offset:51200
	ds_read_b128 v[196:199], v178 offset:52224
	ds_read_b128 v[200:203], v178 offset:53248
	ds_read_b128 v[204:207], v178 offset:54272
	ds_read_b128 v[208:211], v178 offset:55296
	ds_read_b128 v[212:215], v178 offset:56320
	s_add_u32 s26, s26, 0x80
	s_addc_u32 s27, s27, 0
	global_load_lds_dwordx4 v152, s[26:27]
	s_add_i32 m0, s28, 0x2000
	s_add_i32 s28, s51, s31
	global_load_lds_dwordx4 v156, s[26:27]
	s_add_u32 s26, s26, 0x2b0000
	s_addc_u32 s27, s27, 0
	s_mov_b32 m0, s28
	s_nop 0
	global_load_lds_dwordx4 v152, s[26:27]
	s_add_i32 m0, s28, 0x2000
	s_nop 0
	global_load_lds_dwordx4 v156, s[26:27]
	s_mov_b32 m0, s38
	s_nop 0
	global_load_lds_dwordx4 v150, s[98:99]
	s_mov_b32 m0, s39
	s_nop 0
	global_load_lds_dwordx4 v154, s[98:99]
	s_waitcnt vmcnt(8)
	s_waitcnt lgkmcnt(0)
	s_barrier
	s_setprio 1
	s_waitcnt lgkmcnt(0)
	v_mfma_f32_16x16x32_bf16 v[62:65], v[130:133], v[184:187], v[62:65]
	v_mfma_f32_16x16x32_bf16 v[62:65], v[134:137], v[188:191], v[62:65]
	v_mfma_f32_16x16x32_bf16 v[58:61], v[138:141], v[184:187], v[58:61]
	v_mfma_f32_16x16x32_bf16 v[58:61], v[142:145], v[188:191], v[58:61]
	v_mfma_f32_16x16x32_bf16 v[46:49], v[130:133], v[192:195], v[46:49]
	v_mfma_f32_16x16x32_bf16 v[46:49], v[134:137], v[196:199], v[46:49]
	v_mfma_f32_16x16x32_bf16 v[42:45], v[138:141], v[192:195], v[42:45]
	v_mfma_f32_16x16x32_bf16 v[42:45], v[142:145], v[196:199], v[42:45]
	v_mfma_f32_16x16x32_bf16 v[30:33], v[130:133], v[200:203], v[30:33]
	v_mfma_f32_16x16x32_bf16 v[30:33], v[134:137], v[204:207], v[30:33]
	v_mfma_f32_16x16x32_bf16 v[26:29], v[138:141], v[200:203], v[26:29]
	v_mfma_f32_16x16x32_bf16 v[26:29], v[142:145], v[204:207], v[26:29]
	v_mfma_f32_16x16x32_bf16 v[14:17], v[130:133], v[208:211], v[14:17]
	v_mfma_f32_16x16x32_bf16 v[14:17], v[134:137], v[212:215], v[14:17]
	v_mfma_f32_16x16x32_bf16 v[10:13], v[138:141], v[208:211], v[10:13]
	v_mfma_f32_16x16x32_bf16 v[10:13], v[142:145], v[212:215], v[10:13]
	s_setprio 0
	s_setprio 1
	v_mfma_f32_16x16x32_bf16 v[54:57], v[146:149], v[184:187], v[54:57]
	v_mfma_f32_16x16x32_bf16 v[54:57], v[166:169], v[188:191], v[54:57]
	v_mfma_f32_16x16x32_bf16 v[50:53], v[170:173], v[184:187], v[50:53]
	v_mfma_f32_16x16x32_bf16 v[50:53], v[180:183], v[188:191], v[50:53]
	v_mfma_f32_16x16x32_bf16 v[38:41], v[146:149], v[192:195], v[38:41]
	v_mfma_f32_16x16x32_bf16 v[38:41], v[166:169], v[196:199], v[38:41]
	v_mfma_f32_16x16x32_bf16 v[34:37], v[170:173], v[192:195], v[34:37]
	v_mfma_f32_16x16x32_bf16 v[34:37], v[180:183], v[196:199], v[34:37]
	v_mfma_f32_16x16x32_bf16 v[22:25], v[146:149], v[200:203], v[22:25]
	v_mfma_f32_16x16x32_bf16 v[22:25], v[166:169], v[204:207], v[22:25]
	v_mfma_f32_16x16x32_bf16 v[18:21], v[170:173], v[200:203], v[18:21]
	v_mfma_f32_16x16x32_bf16 v[18:21], v[180:183], v[204:207], v[18:21]
	v_mfma_f32_16x16x32_bf16 v[6:9], v[146:149], v[208:211], v[6:9]
	v_mfma_f32_16x16x32_bf16 v[6:9], v[166:169], v[212:215], v[6:9]
	v_mfma_f32_16x16x32_bf16 v[2:5], v[170:173], v[208:211], v[2:5]
	v_mfma_f32_16x16x32_bf16 v[2:5], v[180:183], v[212:215], v[2:5]
	s_setprio 0
	s_barrier
	s_add_i32 s49, s49, 2
	s_add_u32 s24, s24, 0x100
	s_addc_u32 s25, s25, 0
	s_add_u32 s47, s47, 0x100
	s_addc_u32 s48, s48, 0
	s_cmpk_gt_u32 s49, 0xa9
	s_cbranch_scc0 .LBB0_1325
	s_and_b64 vcc, exec, s[10:11]
	s_cbranch_vccz .LBB0_1328
	s_barrier
